# v10glaS
# baseline (speedup 1.0000x reference)
; #define SFLOAD(F_, dvb_) do { _Pragma("unroll") for (int ks = 0; ks < 8; ++ks) F_[ks] = *(const bf16x8*)(sp + (size_t)(dvb_) * 32 * 128 + ks * 16); } while (0)
; #define SFMMA(F_, dvb_) do { _Pragma("unroll") for (int ks = 0; ks < 8; ++ks) o[dvb_] = __builtin_amdgcn_mfma_f32_32x32x16_bf16(F_[ks], qf[ks], o[dvb_], 0, 0, 0); } while (0)
; __device__ __forceinline__ void gla_out(const Params& p, LAS unsigned char* lds, int l) {
;     ...
;             { const bf16_t* qp = proj + (size_t)(tok0 + 32 * ib + r32) * NP + C_QC + h * 128 + hi * 8;
; #pragma unroll
;               for (int ks = 0; ks < 8; ++ks) qf[ks] = *(const bf16x8*)(qp + ks * 16); }
;             { bf16x8 sfA[8];
;     ...
; #pragma unroll
;               for (int d2 = 0; d2 < 8; ++d2) { SFLOAD(sfA, d2); SFMMA(sfA, d2); asm volatile("" ::: "memory"); }
.LBB0_342:
	s_or_b64 exec, exec, s[12:13]
	s_ashr_i32 s35, s34, 31
	s_lshl_b64 s[0:1], s[34:35], 18
	v_lshl_add_u64 v[178:179], v[168:169], 0, s[0:1]
	global_load_dwordx4 v[130:133], v[158:159], off
	global_load_dwordx4 v[134:137], v[158:159], off offset:32
	global_load_dwordx4 v[138:141], v[158:159], off offset:64
	global_load_dwordx4 v[142:145], v[158:159], off offset:96
	global_load_dwordx4 v[146:149], v[158:159], off offset:128
	global_load_dwordx4 v[150:153], v[158:159], off offset:160
	global_load_dwordx4 v[154:157], v[158:159], off offset:192
	s_nop 0
	global_load_dwordx4 v[158:161], v[158:159], off offset:224
	s_nop 0
	global_load_dwordx4 v[184:187], v[178:179], off
	global_load_dwordx4 v[188:191], v[178:179], off offset:32
	global_load_dwordx4 v[192:195], v[178:179], off offset:64
	global_load_dwordx4 v[200:203], v[178:179], off offset:96
	global_load_dwordx4 v[204:207], v[178:179], off offset:128
	global_load_dwordx4 v[208:211], v[178:179], off offset:160
	global_load_dwordx4 v[212:215], v[178:179], off offset:192
	global_load_dwordx4 v[218:221], v[178:179], off offset:224
	v_add_co_u32_e32 v196, vcc, s33, v178
	s_movk_i32 s0, 0x4000
	s_nop 0
	v_addc_co_u32_e32 v197, vcc, 0, v179, vcc
	v_mov_b32_e32 v175, v1
	s_waitcnt vmcnt(7)
	v_mfma_f32_32x32x16_bf16 v[114:129], v[184:187], v[130:133], v[114:129]
	global_load_dwordx4 v[184:187], v[196:197], off
	s_waitcnt vmcnt(7)
	v_mfma_f32_32x32x16_bf16 v[114:129], v[188:191], v[134:137], v[114:129]
	global_load_dwordx4 v[188:191], v[196:197], off offset:32
	s_waitcnt vmcnt(7)
	v_mfma_f32_32x32x16_bf16 v[114:129], v[192:195], v[138:141], v[114:129]
	global_load_dwordx4 v[192:195], v[196:197], off offset:64
	s_waitcnt vmcnt(7)
	v_mfma_f32_32x32x16_bf16 v[114:129], v[200:203], v[142:145], v[114:129]
	global_load_dwordx4 v[200:203], v[196:197], off offset:96
	s_waitcnt vmcnt(7)
	v_mfma_f32_32x32x16_bf16 v[114:129], v[204:207], v[146:149], v[114:129]
	global_load_dwordx4 v[204:207], v[196:197], off offset:128
	s_waitcnt vmcnt(7)
	v_mfma_f32_32x32x16_bf16 v[114:129], v[208:211], v[150:153], v[114:129]
	global_load_dwordx4 v[208:211], v[196:197], off offset:160
	s_waitcnt vmcnt(7)
	v_mfma_f32_32x32x16_bf16 v[114:129], v[212:215], v[154:157], v[114:129]
	global_load_dwordx4 v[212:215], v[196:197], off offset:192
	s_waitcnt vmcnt(7)
	v_mfma_f32_32x32x16_bf16 v[114:129], v[218:221], v[158:161], v[114:129]
	global_load_dwordx4 v[218:221], v[196:197], off offset:224
	v_add_co_u32_e32 v196, vcc, s0, v178
	s_movk_i32 s0, 0x6000
	s_nop 0
	v_addc_co_u32_e32 v197, vcc, 0, v179, vcc
	s_waitcnt vmcnt(7)
	v_mfma_f32_32x32x16_bf16 v[98:113], v[184:187], v[130:133], v[98:113]
	global_load_dwordx4 v[184:187], v[196:197], off
	s_waitcnt vmcnt(7)
	v_mfma_f32_32x32x16_bf16 v[98:113], v[188:191], v[134:137], v[98:113]
	global_load_dwordx4 v[188:191], v[196:197], off offset:32
	s_waitcnt vmcnt(7)
	v_mfma_f32_32x32x16_bf16 v[98:113], v[192:195], v[138:141], v[98:113]
	global_load_dwordx4 v[192:195], v[196:197], off offset:64
	s_waitcnt vmcnt(7)
	v_mfma_f32_32x32x16_bf16 v[98:113], v[200:203], v[142:145], v[98:113]
	global_load_dwordx4 v[200:203], v[196:197], off offset:96
	s_waitcnt vmcnt(7)
	v_mfma_f32_32x32x16_bf16 v[98:113], v[204:207], v[146:149], v[98:113]
	global_load_dwordx4 v[204:207], v[196:197], off offset:128
	s_waitcnt vmcnt(7)
	v_mfma_f32_32x32x16_bf16 v[98:113], v[208:211], v[150:153], v[98:113]
	global_load_dwordx4 v[208:211], v[196:197], off offset:160
	s_waitcnt vmcnt(7)
	v_mfma_f32_32x32x16_bf16 v[98:113], v[212:215], v[154:157], v[98:113]
	global_load_dwordx4 v[212:215], v[196:197], off offset:192
	s_waitcnt vmcnt(7)
	v_mfma_f32_32x32x16_bf16 v[98:113], v[218:221], v[158:161], v[98:113]
	global_load_dwordx4 v[218:221], v[196:197], off offset:224
	v_add_co_u32_e32 v196, vcc, s0, v178
	s_mov_b32 s0, 0x8000
	s_nop 0
	v_addc_co_u32_e32 v197, vcc, 0, v179, vcc
	s_waitcnt vmcnt(7)
	v_mfma_f32_32x32x16_bf16 v[82:97], v[184:187], v[130:133], v[82:97]
	global_load_dwordx4 v[184:187], v[196:197], off
	s_waitcnt vmcnt(7)
	v_mfma_f32_32x32x16_bf16 v[82:97], v[188:191], v[134:137], v[82:97]
	global_load_dwordx4 v[188:191], v[196:197], off offset:32
	s_waitcnt vmcnt(7)
	v_mfma_f32_32x32x16_bf16 v[82:97], v[192:195], v[138:141], v[82:97]
	global_load_dwordx4 v[192:195], v[196:197], off offset:64
	s_waitcnt vmcnt(7)
	v_mfma_f32_32x32x16_bf16 v[82:97], v[200:203], v[142:145], v[82:97]
	global_load_dwordx4 v[200:203], v[196:197], off offset:96
	s_waitcnt vmcnt(7)
	v_mfma_f32_32x32x16_bf16 v[82:97], v[204:207], v[146:149], v[82:97]
	global_load_dwordx4 v[204:207], v[196:197], off offset:128
	s_waitcnt vmcnt(7)
	v_mfma_f32_32x32x16_bf16 v[82:97], v[208:211], v[150:153], v[82:97]
	global_load_dwordx4 v[208:211], v[196:197], off offset:160
	s_waitcnt vmcnt(7)
	v_mfma_f32_32x32x16_bf16 v[82:97], v[212:215], v[154:157], v[82:97]
	global_load_dwordx4 v[212:215], v[196:197], off offset:192
	s_waitcnt vmcnt(7)
	v_mfma_f32_32x32x16_bf16 v[82:97], v[218:221], v[158:161], v[82:97]
	global_load_dwordx4 v[218:221], v[196:197], off offset:224
	v_add_co_u32_e32 v196, vcc, s0, v178
	s_mov_b32 s0, 0xa000
	s_nop 0
	v_addc_co_u32_e32 v197, vcc, 0, v179, vcc
	s_waitcnt vmcnt(7)
	v_mfma_f32_32x32x16_bf16 v[66:81], v[184:187], v[130:133], v[66:81]
	global_load_dwordx4 v[184:187], v[196:197], off
	s_waitcnt vmcnt(7)
	v_mfma_f32_32x32x16_bf16 v[66:81], v[188:191], v[134:137], v[66:81]
	global_load_dwordx4 v[188:191], v[196:197], off offset:32
	s_waitcnt vmcnt(7)
	v_mfma_f32_32x32x16_bf16 v[66:81], v[192:195], v[138:141], v[66:81]
	global_load_dwordx4 v[192:195], v[196:197], off offset:64
	s_waitcnt vmcnt(7)
; #define SFLOAD(F_, dvb_) do { _Pragma("unroll") for (int ks = 0; ks < 8; ++ks) F_[ks] = *(const bf16x8*)(sp + (size_t)(dvb_) * 32 * 128 + ks * 16); } while (0)
; #define SFMMA(F_, dvb_) do { _Pragma("unroll") for (int ks = 0; ks < 8; ++ks) o[dvb_] = __builtin_amdgcn_mfma_f32_32x32x16_bf16(F_[ks], qf[ks], o[dvb_], 0, 0, 0); } while (0)
; __device__ __forceinline__ void gla_out(const Params& p, LAS unsigned char* lds, int l) {
;     ...
;             { const bf16_t* qp = proj + (size_t)(tok0 + 32 * ib + r32) * NP + C_QC + h * 128 + hi * 8;
; #pragma unroll
;               for (int ks = 0; ks < 8; ++ks) qf[ks] = *(const bf16x8*)(qp + ks * 16); }
;             { bf16x8 sfA[8];
;     ...
; #pragma unroll
;               for (int d2 = 0; d2 < 8; ++d2) { SFLOAD(sfA, d2); SFMMA(sfA, d2); asm volatile("" ::: "memory"); }
	v_mfma_f32_32x32x16_bf16 v[66:81], v[200:203], v[142:145], v[66:81]
	global_load_dwordx4 v[200:203], v[196:197], off offset:96
	s_waitcnt vmcnt(7)
	v_mfma_f32_32x32x16_bf16 v[66:81], v[204:207], v[146:149], v[66:81]
	global_load_dwordx4 v[204:207], v[196:197], off offset:128
	s_waitcnt vmcnt(7)
	v_mfma_f32_32x32x16_bf16 v[66:81], v[208:211], v[150:153], v[66:81]
	global_load_dwordx4 v[208:211], v[196:197], off offset:160
	s_waitcnt vmcnt(7)
	v_mfma_f32_32x32x16_bf16 v[66:81], v[212:215], v[154:157], v[66:81]
	global_load_dwordx4 v[212:215], v[196:197], off offset:192
	s_waitcnt vmcnt(7)
	v_mfma_f32_32x32x16_bf16 v[66:81], v[218:221], v[158:161], v[66:81]
	global_load_dwordx4 v[218:221], v[196:197], off offset:224
	v_add_co_u32_e32 v196, vcc, s0, v178
	s_mov_b32 s0, 0xc000
	s_nop 0
	v_addc_co_u32_e32 v197, vcc, 0, v179, vcc
	s_waitcnt vmcnt(7)
	v_mfma_f32_32x32x16_bf16 v[50:65], v[184:187], v[130:133], v[50:65]
	global_load_dwordx4 v[184:187], v[196:197], off
	s_waitcnt vmcnt(7)
	v_mfma_f32_32x32x16_bf16 v[50:65], v[188:191], v[134:137], v[50:65]
	global_load_dwordx4 v[188:191], v[196:197], off offset:32
	s_waitcnt vmcnt(7)
	v_mfma_f32_32x32x16_bf16 v[50:65], v[192:195], v[138:141], v[50:65]
	global_load_dwordx4 v[192:195], v[196:197], off offset:64
	s_waitcnt vmcnt(7)
	v_mfma_f32_32x32x16_bf16 v[50:65], v[200:203], v[142:145], v[50:65]
	global_load_dwordx4 v[200:203], v[196:197], off offset:96
	s_waitcnt vmcnt(7)
	v_mfma_f32_32x32x16_bf16 v[50:65], v[204:207], v[146:149], v[50:65]
	global_load_dwordx4 v[204:207], v[196:197], off offset:128
	s_waitcnt vmcnt(7)
	v_mfma_f32_32x32x16_bf16 v[50:65], v[208:211], v[150:153], v[50:65]
	global_load_dwordx4 v[208:211], v[196:197], off offset:160
	s_waitcnt vmcnt(7)
	v_mfma_f32_32x32x16_bf16 v[50:65], v[212:215], v[154:157], v[50:65]
	global_load_dwordx4 v[212:215], v[196:197], off offset:192
	s_waitcnt vmcnt(7)
	v_mfma_f32_32x32x16_bf16 v[50:65], v[218:221], v[158:161], v[50:65]
	global_load_dwordx4 v[218:221], v[196:197], off offset:224
	v_add_co_u32_e32 v196, vcc, s0, v178
	s_mov_b32 s0, 0xe000
	s_nop 0
	v_addc_co_u32_e32 v197, vcc, 0, v179, vcc
	v_add_co_u32_e32 v178, vcc, s0, v178
	s_mov_b64 s[0:1], 0x30a0
	s_nop 0
	v_addc_co_u32_e32 v179, vcc, 0, v179, vcc
	s_waitcnt vmcnt(7)
	v_mfma_f32_32x32x16_bf16 v[34:49], v[184:187], v[130:133], v[34:49]
	global_load_dwordx4 v[184:187], v[196:197], off
	s_waitcnt vmcnt(7)
	v_mfma_f32_32x32x16_bf16 v[34:49], v[188:191], v[134:137], v[34:49]
	global_load_dwordx4 v[188:191], v[196:197], off offset:32
	s_waitcnt vmcnt(7)
	v_mfma_f32_32x32x16_bf16 v[34:49], v[192:195], v[138:141], v[34:49]
	global_load_dwordx4 v[192:195], v[196:197], off offset:64
	s_waitcnt vmcnt(7)
	v_mfma_f32_32x32x16_bf16 v[34:49], v[200:203], v[142:145], v[34:49]
	global_load_dwordx4 v[200:203], v[196:197], off offset:96
	s_waitcnt vmcnt(7)
	v_mfma_f32_32x32x16_bf16 v[34:49], v[204:207], v[146:149], v[34:49]
	global_load_dwordx4 v[204:207], v[196:197], off offset:128
	s_waitcnt vmcnt(7)
	v_mfma_f32_32x32x16_bf16 v[34:49], v[208:211], v[150:153], v[34:49]
	global_load_dwordx4 v[208:211], v[196:197], off offset:160
	s_waitcnt vmcnt(7)
	v_mfma_f32_32x32x16_bf16 v[34:49], v[212:215], v[154:157], v[34:49]
	global_load_dwordx4 v[212:215], v[196:197], off offset:192
	s_waitcnt vmcnt(7)
	v_mfma_f32_32x32x16_bf16 v[34:49], v[218:221], v[158:161], v[34:49]
	global_load_dwordx4 v[218:221], v[196:197], off offset:224
	s_waitcnt vmcnt(7)
	v_mfma_f32_32x32x16_bf16 v[18:33], v[184:187], v[130:133], v[18:33]
	s_waitcnt vmcnt(6)
	v_mfma_f32_32x32x16_bf16 v[18:33], v[188:191], v[134:137], v[18:33]
	s_waitcnt vmcnt(5)
	v_mfma_f32_32x32x16_bf16 v[18:33], v[192:195], v[138:141], v[18:33]
	s_waitcnt vmcnt(4)
	v_mfma_f32_32x32x16_bf16 v[18:33], v[200:203], v[142:145], v[18:33]
	s_waitcnt vmcnt(3)
	v_mfma_f32_32x32x16_bf16 v[18:33], v[204:207], v[146:149], v[18:33]
	s_waitcnt vmcnt(2)
	v_mfma_f32_32x32x16_bf16 v[18:33], v[208:211], v[150:153], v[18:33]
	s_waitcnt vmcnt(1)
	v_mfma_f32_32x32x16_bf16 v[18:33], v[212:215], v[154:157], v[18:33]
	s_waitcnt vmcnt(0)
	v_mfma_f32_32x32x16_bf16 v[18:33], v[218:221], v[158:161], v[18:33]
	global_load_dwordx4 v[184:187], v[178:179], off
	global_load_dwordx4 v[188:191], v[178:179], off offset:32
	global_load_dwordx4 v[192:195], v[178:179], off offset:64
	global_load_dwordx4 v[200:203], v[178:179], off offset:96
	global_load_dwordx4 v[204:207], v[178:179], off offset:128
	global_load_dwordx4 v[208:211], v[178:179], off offset:160
	global_load_dwordx4 v[212:215], v[178:179], off offset:192
	global_load_dwordx4 v[218:221], v[178:179], off offset:224
	s_waitcnt vmcnt(7)
	v_mfma_f32_32x32x16_bf16 v[2:17], v[184:187], v[130:133], v[2:17]
	s_waitcnt vmcnt(6)
	v_mfma_f32_32x32x16_bf16 v[2:17], v[188:191], v[134:137], v[2:17]
	s_waitcnt vmcnt(5)
; #define SFLOAD(F_, dvb_) do { _Pragma("unroll") for (int ks = 0; ks < 8; ++ks) F_[ks] = *(const bf16x8*)(sp + (size_t)(dvb_) * 32 * 128 + ks * 16); } while (0)
; #define SFMMA(F_, dvb_) do { _Pragma("unroll") for (int ks = 0; ks < 8; ++ks) o[dvb_] = __builtin_amdgcn_mfma_f32_32x32x16_bf16(F_[ks], qf[ks], o[dvb_], 0, 0, 0); } while (0)
; __device__ __forceinline__ void gla_out(const Params& p, LAS unsigned char* lds, int l) {
;     ...
;               for (int d2 = 0; d2 < 8; ++d2) { SFLOAD(sfA, d2); SFMMA(sfA, d2); asm volatile("" ::: "memory"); }
;     ...
;             }
;             float ss = 0.f;
; #pragma unroll
;             for (int dvb = 0; dvb < 8; ++dvb)
; #pragma unroll
;                 for (int r = 0; r < 16; ++r) ss += o[dvb][r] * o[dvb][r];
;             ss += __shfl_xor(ss, 32);
;             const float rs = rsqrtf(ss * (1.f / 256.f) + EPS);
	v_mfma_f32_32x32x16_bf16 v[2:17], v[192:195], v[138:141], v[2:17]
	v_mul_f32_e32 v140, v115, v115
	v_fmac_f32_e32 v140, v114, v114
	v_fmac_f32_e32 v140, v116, v116
	v_fmac_f32_e32 v140, v117, v117
	v_fmac_f32_e32 v140, v118, v118
	v_fmac_f32_e32 v140, v119, v119
	v_fmac_f32_e32 v140, v120, v120
	v_fmac_f32_e32 v140, v121, v121
	v_fmac_f32_e32 v140, v122, v122
	v_fmac_f32_e32 v140, v123, v123
	v_fmac_f32_e32 v140, v124, v124
	v_fmac_f32_e32 v140, v125, v125
	v_fmac_f32_e32 v140, v126, v126
	v_fmac_f32_e32 v140, v127, v127
	v_fmac_f32_e32 v140, v128, v128
	v_fmac_f32_e32 v140, v129, v129
	v_fmac_f32_e32 v140, v98, v98
	v_fmac_f32_e32 v140, v99, v99
	v_fmac_f32_e32 v140, v100, v100
	v_fmac_f32_e32 v140, v101, v101
	v_fmac_f32_e32 v140, v102, v102
	v_fmac_f32_e32 v140, v103, v103
	v_fmac_f32_e32 v140, v104, v104
	v_fmac_f32_e32 v140, v105, v105
	v_fmac_f32_e32 v140, v106, v106
	v_fmac_f32_e32 v140, v107, v107
	v_fmac_f32_e32 v140, v108, v108
	v_fmac_f32_e32 v140, v109, v109
	v_fmac_f32_e32 v140, v110, v110
	v_fmac_f32_e32 v140, v111, v111
	v_fmac_f32_e32 v140, v112, v112
	v_fmac_f32_e32 v140, v113, v113
	v_fmac_f32_e32 v140, v82, v82
	v_fmac_f32_e32 v140, v83, v83
	v_fmac_f32_e32 v140, v84, v84
	v_fmac_f32_e32 v140, v85, v85
	v_fmac_f32_e32 v140, v86, v86
	v_fmac_f32_e32 v140, v87, v87
	v_fmac_f32_e32 v140, v88, v88
	v_fmac_f32_e32 v140, v89, v89
	v_fmac_f32_e32 v140, v90, v90
	v_fmac_f32_e32 v140, v91, v91
	v_fmac_f32_e32 v140, v92, v92
	v_fmac_f32_e32 v140, v93, v93
	v_fmac_f32_e32 v140, v94, v94
	v_fmac_f32_e32 v140, v95, v95
	v_fmac_f32_e32 v140, v96, v96
	v_fmac_f32_e32 v140, v97, v97
	v_fmac_f32_e32 v140, v66, v66
	v_fmac_f32_e32 v140, v67, v67
	v_fmac_f32_e32 v140, v68, v68
	v_fmac_f32_e32 v140, v69, v69
	v_fmac_f32_e32 v140, v70, v70
	v_fmac_f32_e32 v140, v71, v71
	v_fmac_f32_e32 v140, v72, v72
	v_fmac_f32_e32 v140, v73, v73
	v_fmac_f32_e32 v140, v74, v74
	v_fmac_f32_e32 v140, v75, v75
	v_fmac_f32_e32 v140, v76, v76
	v_fmac_f32_e32 v140, v77, v77
	v_fmac_f32_e32 v140, v78, v78
	v_fmac_f32_e32 v140, v79, v79
	v_fmac_f32_e32 v140, v80, v80
	v_fmac_f32_e32 v140, v81, v81
	v_fmac_f32_e32 v140, v50, v50
	v_fmac_f32_e32 v140, v51, v51
	v_fmac_f32_e32 v140, v52, v52
	v_fmac_f32_e32 v140, v53, v53
	v_fmac_f32_e32 v140, v54, v54
	v_fmac_f32_e32 v140, v55, v55
	v_fmac_f32_e32 v140, v56, v56
	v_fmac_f32_e32 v140, v57, v57
	s_waitcnt vmcnt(4)
	v_mfma_f32_32x32x16_bf16 v[2:17], v[200:203], v[142:145], v[2:17]
	v_fmac_f32_e32 v140, v58, v58
	v_fmac_f32_e32 v140, v59, v59
	v_fmac_f32_e32 v140, v60, v60
	v_fmac_f32_e32 v140, v61, v61
	v_fmac_f32_e32 v140, v62, v62
	v_fmac_f32_e32 v140, v63, v63
	v_fmac_f32_e32 v140, v64, v64
	v_fmac_f32_e32 v140, v65, v65
	s_waitcnt vmcnt(3)
	v_mfma_f32_32x32x16_bf16 v[2:17], v[204:207], v[146:149], v[2:17]
	v_fmac_f32_e32 v140, v34, v34
	v_fmac_f32_e32 v140, v35, v35
	v_fmac_f32_e32 v140, v36, v36
	v_fmac_f32_e32 v140, v37, v37
	v_fmac_f32_e32 v140, v38, v38
	v_fmac_f32_e32 v140, v39, v39
	v_fmac_f32_e32 v140, v40, v40
	v_fmac_f32_e32 v140, v41, v41
	s_waitcnt vmcnt(2)
	v_mfma_f32_32x32x16_bf16 v[2:17], v[208:211], v[150:153], v[2:17]
	v_fmac_f32_e32 v140, v42, v42
	v_fmac_f32_e32 v140, v43, v43
	v_fmac_f32_e32 v140, v44, v44
	v_fmac_f32_e32 v140, v45, v45
	v_fmac_f32_e32 v140, v46, v46
	v_fmac_f32_e32 v140, v47, v47
	v_fmac_f32_e32 v140, v48, v48
	v_fmac_f32_e32 v140, v49, v49
	s_waitcnt vmcnt(1)
	v_mfma_f32_32x32x16_bf16 v[2:17], v[212:215], v[154:157], v[2:17]
	v_fmac_f32_e32 v140, v18, v18
	v_fmac_f32_e32 v140, v19, v19
	v_fmac_f32_e32 v140, v20, v20
	v_fmac_f32_e32 v140, v21, v21
	v_fmac_f32_e32 v140, v22, v22
	v_fmac_f32_e32 v140, v23, v23
	v_fmac_f32_e32 v140, v24, v24
	v_fmac_f32_e32 v140, v25, v25
	s_waitcnt vmcnt(0)
	v_mfma_f32_32x32x16_bf16 v[2:17], v[218:221], v[158:161], v[2:17]
	v_fmac_f32_e32 v140, v26, v26
	v_fmac_f32_e32 v140, v27, v27
	v_fmac_f32_e32 v140, v28, v28
	v_fmac_f32_e32 v140, v29, v29
	v_fmac_f32_e32 v140, v30, v30
	v_fmac_f32_e32 v140, v31, v31
	v_fmac_f32_e32 v140, v32, v32
	v_fmac_f32_e32 v140, v33, v33
	s_nop 3
	v_fmac_f32_e32 v140, v2, v2
	v_fmac_f32_e32 v140, v3, v3
	v_fmac_f32_e32 v140, v4, v4
	v_fmac_f32_e32 v140, v5, v5
	v_fmac_f32_e32 v140, v6, v6
	v_fmac_f32_e32 v140, v7, v7
	v_pk_mul_f32 v[138:139], v[8:9], v[8:9]
	v_pk_mul_f32 v[136:137], v[10:11], v[10:11]
	v_add_f32_e32 v138, v138, v140
	v_add_f32_e32 v138, v139, v138
	v_add_f32_e32 v136, v136, v138
	v_pk_mul_f32 v[134:135], v[12:13], v[12:13]
	v_add_f32_e32 v136, v137, v136
	v_add_f32_e32 v134, v134, v136
	v_pk_mul_f32 v[132:133], v[14:15], v[14:15]
	v_add_f32_e32 v134, v135, v134
	v_add_f32_e32 v132, v132, v134
	v_pk_mul_f32 v[130:131], v[16:17], v[16:17]
	v_add_f32_e32 v132, v133, v132
	v_add_f32_e32 v130, v130, v132
	v_and_b32_e32 v132, 64, v252
	v_add_f32_e32 v130, v131, v130
	v_xor_b32_e32 v131, 32, v252
	v_add_u32_e32 v132, 64, v132
	v_cmp_lt_i32_e32 vcc, v131, v132
	s_nop 1
	v_cndmask_b32_e32 v131, v252, v131, vcc
	v_lshlrev_b32_e32 v131, 2, v131
	ds_bpermute_b32 v131, v131, v130
	s_waitcnt lgkmcnt(0)
	v_add_f32_e32 v130, v130, v131
	v_fmamk_f32 v130, v130, 0x3b800000, v198
	v_cmp_gt_f32_e32 vcc, s28, v130
	v_mul_f32_e32 v131, 0x4b800000, v130
	s_nop 0
	v_cndmask_b32_e32 v130, v130, v131, vcc
	v_rsq_f32_e32 v130, v130
	s_nop 0
	v_mul_f32_e32 v131, 0x45800000, v130
	v_cndmask_b32_e32 v140, v130, v131, vcc
	v_lshl_add_u64 v[130:131], v[164:165], 1, v[176:177]
	v_lshl_add_u64 v[130:131], v[130:131], 0, v[174:175]
	v_add_co_u32_e32 v136, vcc, s53, v130
	v_lshl_add_u64 v[134:135], v[130:131], 0, s[0:1]
	s_nop 0
	v_addc_co_u32_e32 v137, vcc, 0, v131, vcc
	global_load_dwordx2 v[138:139], v[136:137], off offset:160
	global_load_dwordx4 v[130:133], v[170:171], off
	v_mul_f32_e32 v143, v114, v140
	v_mul_f32_e32 v115, v115, v140
	v_mul_f32_e32 v119, v119, v140
	s_mov_b32 s0, s96
	s_waitcnt vmcnt(1)
; __device__ __forceinline__ unsigned cvt_pk_bf16(float lo, float hi) { unsigned r; asm volatile("v_cvt_pk_bf16_f32 %0, %1, %2" : "=v"(r) : "v"(lo), "v"(hi)); return r; }
; __device__ __forceinline__ float bf_lo(unsigned w) { return __uint_as_float(w << 16); }
; __device__ __forceinline__ float bf_hi(unsigned w) { return __uint_as_float(w & 0xffff0000u); }
; __device__ __forceinline__ float siluf_(float v) { return v * sigmoidf_(v); }
; __device__ __forceinline__ void gla_out(const Params& p, LAS unsigned char* lds, int l) {
;     ...
;             bf16_t* zp = proj + (size_t)(tok0 + 32 * ib + r32) * NP + C_ZC + h * 256; const float* gn = p.gla_norm + l * 1024 + h * 256;
; #pragma unroll
;             for (int dvb = 0; dvb < 8; ++dvb)
; #pragma unroll
;                 for (int rq = 0; rq < 4; ++rq) { const int dv = dvb * 32 + 8 * rq + 4 * hi; const u32x2 zz = *(const u32x2*)(zp + dv); const f32x4 g4 = *(const f32x4*)(gn + dv);
;                     const float y0 = o[dvb][rq * 4 + 0] * rs * g4[0] * siluf_(bf_lo(zz.x)), y1 = o[dvb][rq * 4 + 1] * rs * g4[1] * siluf_(bf_hi(zz.x));
;                     const float y2 = o[dvb][rq * 4 + 2] * rs * g4[2] * siluf_(bf_lo(zz.y)), y3 = o[dvb][rq * 4 + 3] * rs * g4[3] * siluf_(bf_hi(zz.y));
;                     u32x2 w; w.x = cvt_pk_bf16(y0, y1); w.y = cvt_pk_bf16(y2, y3); *(u32x2*)(zp + dv) = w; }
	v_lshlrev_b32_e32 v142, 16, v138
	v_mul_f32_e32 v114, 0xbfb8aa3b, v142
	v_exp_f32_e32 v114, v114
	s_waitcnt vmcnt(0)
	v_mov_b32_e32 v145, v130
	v_add_f32_e32 v114, 1.0, v114
	v_rcp_f32_e32 v144, v114
	v_and_b32_e32 v114, 0xffff0000, v138
	v_mul_f32_e32 v130, 0xbfb8aa3b, v114
	v_exp_f32_e32 v130, v130
	v_pk_mul_f32 v[142:143], v[144:145], v[142:143]
	v_add_f32_e32 v130, 1.0, v130
	v_rcp_f32_e32 v130, v130
	v_mul_f32_e32 v141, v142, v143
	v_pk_mul_f32 v[114:115], v[130:131], v[114:115]
	s_nop 0
	v_mul_f32_e32 v138, v114, v115
	v_lshlrev_b32_e32 v114, 16, v139
	v_mul_f32_e32 v115, v116, v140
	v_mul_f32_e32 v116, 0xbfb8aa3b, v114
	v_exp_f32_e32 v116, v116
	v_mov_b32_e32 v131, v132
	v_add_f32_e32 v116, 1.0, v116
	v_rcp_f32_e32 v130, v116
	s_nop 0
	v_pk_mul_f32 v[114:115], v[130:131], v[114:115]
	s_nop 0
	v_mul_f32_e32 v116, v114, v115
	v_and_b32_e32 v114, 0xffff0000, v139
	v_mul_f32_e32 v115, v117, v140
	v_mul_f32_e32 v117, 0xbfb8aa3b, v114
	v_exp_f32_e32 v117, v117
	s_nop 0
	v_add_f32_e32 v117, 1.0, v117
	v_rcp_f32_e32 v132, v117
	s_nop 0
	v_pk_mul_f32 v[114:115], v[132:133], v[114:115]
	s_nop 0
	v_mul_f32_e32 v115, v114, v115
	v_cvt_pk_bf16_f32 v114, v141, v138
	v_cvt_pk_bf16_f32 v115, v116, v115
	global_store_dwordx2 v[136:137], v[114:115], off offset:160
	global_load_dwordx2 v[130:131], v[134:135], off offset:16
	s_nop 0
	global_load_dwordx4 v[114:117], v[170:171], off offset:32
	v_mul_f32_e32 v133, v118, v140
	s_waitcnt vmcnt(1)
	v_lshlrev_b32_e32 v132, 16, v130
	v_mul_f32_e32 v118, 0xbfb8aa3b, v132
	v_exp_f32_e32 v118, v118
	s_waitcnt vmcnt(0)
	v_mov_b32_e32 v137, v114
	v_add_f32_e32 v118, 1.0, v118
	v_rcp_f32_e32 v136, v118
	v_and_b32_e32 v118, 0xffff0000, v130
	v_mul_f32_e32 v114, 0xbfb8aa3b, v118
	v_exp_f32_e32 v114, v114
	v_pk_mul_f32 v[132:133], v[136:137], v[132:133]
	v_add_f32_e32 v114, 1.0, v114
	v_rcp_f32_e32 v114, v114
	v_mul_f32_e32 v132, v132, v133
	v_pk_mul_f32 v[114:115], v[114:115], v[118:119]
	s_nop 0
	v_mul_f32_e32 v130, v114, v115
	v_lshlrev_b32_e32 v114, 16, v131
	v_mul_f32_e32 v118, 0xbfb8aa3b, v114
	v_exp_f32_e32 v118, v118
	v_mul_f32_e32 v115, v120, v140
	v_mov_b32_e32 v119, v116
	v_add_f32_e32 v118, 1.0, v118
	v_rcp_f32_e32 v118, v118
	s_nop 0
	v_pk_mul_f32 v[114:115], v[118:119], v[114:115]
	s_nop 0
	v_mul_f32_e32 v118, v114, v115
	v_and_b32_e32 v114, 0xffff0000, v131
	v_mul_f32_e32 v116, 0xbfb8aa3b, v114
	v_exp_f32_e32 v116, v116
	v_mul_f32_e32 v115, v121, v140
	v_mul_f32_e32 v121, v122, v140
	v_add_f32_e32 v116, 1.0, v116
	v_rcp_f32_e32 v116, v116
	s_nop 0
	v_pk_mul_f32 v[114:115], v[116:117], v[114:115]
	s_nop 0
	v_mul_f32_e32 v115, v114, v115
	v_cvt_pk_bf16_f32 v114, v132, v130
	v_cvt_pk_bf16_f32 v115, v118, v115
	global_store_dwordx2 v[134:135], v[114:115], off offset:16
	global_load_dwordx2 v[118:119], v[134:135], off offset:32
	s_nop 0
	global_load_dwordx4 v[114:117], v[170:171], off offset:64
	s_waitcnt vmcnt(1)
	v_lshlrev_b32_e32 v120, 16, v118
	v_mul_f32_e32 v122, 0xbfb8aa3b, v120
	v_exp_f32_e32 v122, v122
	s_waitcnt vmcnt(0)
	v_mov_b32_e32 v131, v114
	v_add_f32_e32 v122, 1.0, v122
	v_rcp_f32_e32 v130, v122
	s_nop 0
	v_pk_mul_f32 v[120:121], v[130:131], v[120:121]
	s_nop 0
	v_mul_f32_e32 v122, v120, v121
	v_and_b32_e32 v120, 0xffff0000, v118
	v_mul_f32_e32 v114, 0xbfb8aa3b, v120
	v_exp_f32_e32 v114, v114
	v_mul_f32_e32 v121, v123, v140
	v_add_f32_e32 v114, 1.0, v114
	v_rcp_f32_e32 v114, v114
	s_nop 0
	v_pk_mul_f32 v[114:115], v[114:115], v[120:121]
	s_nop 0
	v_mul_f32_e32 v118, v114, v115
	v_lshlrev_b32_e32 v114, 16, v119
	v_mul_f32_e32 v120, 0xbfb8aa3b, v114
	v_exp_f32_e32 v120, v120
	v_mul_f32_e32 v115, v124, v140
	v_mov_b32_e32 v121, v116
	v_add_f32_e32 v120, 1.0, v120
	v_rcp_f32_e32 v120, v120
	s_nop 0
	v_pk_mul_f32 v[114:115], v[120:121], v[114:115]
	s_nop 0
	v_mul_f32_e32 v120, v114, v115
	v_and_b32_e32 v114, 0xffff0000, v119
	v_mul_f32_e32 v116, 0xbfb8aa3b, v114
	v_exp_f32_e32 v116, v116
	v_mul_f32_e32 v115, v125, v140
	v_mul_f32_e32 v121, v126, v140
	v_add_f32_e32 v116, 1.0, v116
	v_rcp_f32_e32 v116, v116
	s_nop 0
	v_pk_mul_f32 v[114:115], v[116:117], v[114:115]
	s_nop 0
	v_mul_f32_e32 v115, v114, v115
	v_cvt_pk_bf16_f32 v114, v122, v118
	v_cvt_pk_bf16_f32 v115, v120, v115
	global_store_dwordx2 v[134:135], v[114:115], off offset:32
	global_load_dwordx2 v[118:119], v[134:135], off offset:48
	s_nop 0
	global_load_dwordx4 v[114:117], v[170:171], off offset:96
	s_waitcnt vmcnt(1)
	v_lshlrev_b32_e32 v120, 16, v118
	v_mul_f32_e32 v122, 0xbfb8aa3b, v120
	v_exp_f32_e32 v122, v122
	s_waitcnt vmcnt(0)
	v_mov_b32_e32 v123, v114
	v_add_f32_e32 v122, 1.0, v122
	v_rcp_f32_e32 v122, v122
	s_nop 0
	v_pk_mul_f32 v[120:121], v[122:123], v[120:121]
	s_nop 0
	v_mul_f32_e32 v122, v120, v121
	v_and_b32_e32 v120, 0xffff0000, v118
	v_mul_f32_e32 v114, 0xbfb8aa3b, v120
	v_exp_f32_e32 v114, v114
	v_mul_f32_e32 v121, v127, v140
	v_add_f32_e32 v114, 1.0, v114
	v_rcp_f32_e32 v114, v114
	s_nop 0
	v_pk_mul_f32 v[114:115], v[114:115], v[120:121]
	s_nop 0
	v_mul_f32_e32 v118, v114, v115
	v_lshlrev_b32_e32 v114, 16, v119
	v_mul_f32_e32 v120, 0xbfb8aa3b, v114
	v_exp_f32_e32 v120, v120
	v_mul_f32_e32 v115, v128, v140
	v_mov_b32_e32 v121, v116
	v_add_f32_e32 v120, 1.0, v120
	v_rcp_f32_e32 v120, v120
	s_nop 0
	v_pk_mul_f32 v[114:115], v[120:121], v[114:115]
	s_nop 0
	v_mul_f32_e32 v120, v114, v115
	v_and_b32_e32 v114, 0xffff0000, v119
	v_mul_f32_e32 v116, 0xbfb8aa3b, v114
	v_exp_f32_e32 v116, v116
	v_mul_f32_e32 v115, v129, v140
	v_add_f32_e32 v116, 1.0, v116
	v_rcp_f32_e32 v116, v116
	s_nop 0
	v_pk_mul_f32 v[114:115], v[116:117], v[114:115]
	s_nop 0
	v_mul_f32_e32 v115, v114, v115
	v_cvt_pk_bf16_f32 v114, v122, v118
	v_cvt_pk_bf16_f32 v115, v120, v115
	global_store_dwordx2 v[134:135], v[114:115], off offset:48
	global_load_dwordx2 v[118:119], v[134:135], off offset:64
	s_nop 0
	global_load_dwordx4 v[114:117], v[170:171], off offset:128
	v_mul_f32_e32 v120, v98, v140
	s_waitcnt vmcnt(1)
; __device__ __forceinline__ unsigned cvt_pk_bf16(float lo, float hi) { unsigned r; asm volatile("v_cvt_pk_bf16_f32 %0, %1, %2" : "=v"(r) : "v"(lo), "v"(hi)); return r; }
; __device__ __forceinline__ float bf_lo(unsigned w) { return __uint_as_float(w << 16); }
; __device__ __forceinline__ float bf_hi(unsigned w) { return __uint_as_float(w & 0xffff0000u); }
; __device__ __forceinline__ float siluf_(float v) { return v * sigmoidf_(v); }
; __device__ __forceinline__ void gla_out(const Params& p, LAS unsigned char* lds, int l) {
;     ...
;             bf16_t* zp = proj + (size_t)(tok0 + 32 * ib + r32) * NP + C_ZC + h * 256; const float* gn = p.gla_norm + l * 1024 + h * 256;
; #pragma unroll
;             for (int dvb = 0; dvb < 8; ++dvb)
; #pragma unroll
;                 for (int rq = 0; rq < 4; ++rq) { const int dv = dvb * 32 + 8 * rq + 4 * hi; const u32x2 zz = *(const u32x2*)(zp + dv); const f32x4 g4 = *(const f32x4*)(gn + dv);
;                     const float y0 = o[dvb][rq * 4 + 0] * rs * g4[0] * siluf_(bf_lo(zz.x)), y1 = o[dvb][rq * 4 + 1] * rs * g4[1] * siluf_(bf_hi(zz.x));
;                     const float y2 = o[dvb][rq * 4 + 2] * rs * g4[2] * siluf_(bf_lo(zz.y)), y3 = o[dvb][rq * 4 + 3] * rs * g4[3] * siluf_(bf_hi(zz.y));
;                     u32x2 w; w.x = cvt_pk_bf16(y0, y1); w.y = cvt_pk_bf16(y2, y3); *(u32x2*)(zp + dv) = w; }
	v_lshlrev_b32_e32 v121, 16, v118
	v_mul_f32_e32 v98, 0xbfb8aa3b, v121
	v_exp_f32_e32 v98, v98
	s_waitcnt vmcnt(0)
	v_mov_b32_e32 v122, v114
	v_add_f32_e32 v98, 1.0, v98
	v_rcp_f32_e32 v123, v98
	v_mul_f32_e32 v98, v99, v140
	v_and_b32_e32 v99, 0xffff0000, v118
	v_mul_f32_e32 v114, 0xbfb8aa3b, v99
	v_exp_f32_e32 v114, v114
	v_pk_mul_f32 v[120:121], v[122:123], v[120:121]
	v_add_f32_e32 v114, 1.0, v114
	v_mul_f32_e32 v122, v120, v121
	v_rcp_f32_e32 v121, v114
	v_mov_b32_e32 v120, v115
	v_mov_b32_e32 v114, v116
	v_mul_f32_e32 v116, v102, v140
	v_pk_mul_f32 v[98:99], v[120:121], v[98:99]
	s_nop 0
	v_mul_f32_e32 v118, v98, v99
	v_lshlrev_b32_e32 v99, 16, v119
	v_mul_f32_e32 v98, v100, v140
	v_mul_f32_e32 v100, 0xbfb8aa3b, v99
	v_exp_f32_e32 v100, v100
	s_nop 0
	v_add_f32_e32 v100, 1.0, v100
	v_rcp_f32_e32 v115, v100
	s_nop 0
	v_pk_mul_f32 v[98:99], v[114:115], v[98:99]
	s_nop 0
	v_mul_f32_e32 v114, v98, v99
	v_and_b32_e32 v99, 0xffff0000, v119
	v_mul_f32_e32 v100, 0xbfb8aa3b, v99
	v_exp_f32_e32 v100, v100
	v_mul_f32_e32 v98, v101, v140
	v_add_f32_e32 v100, 1.0, v100
	v_rcp_f32_e32 v101, v100
	v_mov_b32_e32 v100, v117
	v_pk_mul_f32 v[98:99], v[100:101], v[98:99]
	s_nop 0
	v_mul_f32_e32 v99, v98, v99
	v_cvt_pk_bf16_f32 v98, v122, v118
	v_cvt_pk_bf16_f32 v99, v114, v99
	global_store_dwordx2 v[134:135], v[98:99], off offset:64
	global_load_dwordx2 v[114:115], v[134:135], off offset:80
	s_nop 0
	global_load_dwordx4 v[98:101], v[170:171], off offset:160
	s_waitcnt vmcnt(1)
	v_lshlrev_b32_e32 v119, 16, v114
	v_mul_f32_e32 v102, 0xbfb8aa3b, v119
	v_exp_f32_e32 v102, v102
	s_waitcnt vmcnt(0)
	v_mov_b32_e32 v118, v98
	v_add_f32_e32 v102, 1.0, v102
	v_rcp_f32_e32 v117, v102
	v_mul_f32_e32 v102, v103, v140
	v_pk_mul_f32 v[116:117], v[116:117], v[118:119]
	s_nop 0
	v_mul_f32_e32 v118, v116, v117
	v_and_b32_e32 v117, 0xffff0000, v114
	v_mul_f32_e32 v98, 0xbfb8aa3b, v117
	v_exp_f32_e32 v98, v98
	v_mov_b32_e32 v116, v99
	v_add_f32_e32 v98, 1.0, v98
	v_rcp_f32_e32 v103, v98
	s_nop 0
	v_pk_mul_f32 v[98:99], v[102:103], v[116:117]
	v_lshlrev_b32_e32 v103, 16, v115
	v_mul_f32_e32 v114, v98, v99
	v_mul_f32_e32 v99, 0xbfb8aa3b, v103
	v_exp_f32_e32 v99, v99
	v_mul_f32_e32 v98, v104, v140
	v_mov_b32_e32 v102, v100
	v_mul_f32_e32 v104, v106, v140
	v_add_f32_e32 v99, 1.0, v99
	v_rcp_f32_e32 v99, v99
	s_nop 0
	v_pk_mul_f32 v[98:99], v[98:99], v[102:103]
	v_and_b32_e32 v103, 0xffff0000, v115
	v_mul_f32_e32 v100, v98, v99
	v_mul_f32_e32 v99, 0xbfb8aa3b, v103
	v_exp_f32_e32 v99, v99
	v_mul_f32_e32 v98, v105, v140
	v_mov_b32_e32 v102, v101
	v_add_f32_e32 v99, 1.0, v99
	v_rcp_f32_e32 v99, v99
	s_nop 0
	v_pk_mul_f32 v[98:99], v[98:99], v[102:103]
	s_nop 0
	v_mul_f32_e32 v99, v98, v99
	v_cvt_pk_bf16_f32 v98, v118, v114
	v_cvt_pk_bf16_f32 v99, v100, v99
	global_store_dwordx2 v[134:135], v[98:99], off offset:80
	global_load_dwordx2 v[102:103], v[134:135], off offset:96
	s_nop 0
	global_load_dwordx4 v[98:101], v[170:171], off offset:192
	s_waitcnt vmcnt(1)
	v_lshlrev_b32_e32 v115, 16, v102
	v_mul_f32_e32 v105, 0xbfb8aa3b, v115
	v_exp_f32_e32 v105, v105
	s_waitcnt vmcnt(0)
	v_mov_b32_e32 v114, v98
	v_mov_b32_e32 v106, v99
	v_add_f32_e32 v105, 1.0, v105
	v_rcp_f32_e32 v105, v105
	s_nop 0
	v_pk_mul_f32 v[104:105], v[104:105], v[114:115]
	s_nop 0
	v_mul_f32_e32 v114, v104, v105
	v_mul_f32_e32 v104, v107, v140
	v_and_b32_e32 v107, 0xffff0000, v102
	v_mul_f32_e32 v98, 0xbfb8aa3b, v107
	v_exp_f32_e32 v98, v98
	v_mov_b32_e32 v102, v101
	v_add_f32_e32 v98, 1.0, v98
	v_rcp_f32_e32 v105, v98
	s_nop 0
	v_pk_mul_f32 v[98:99], v[104:105], v[106:107]
	v_lshlrev_b32_e32 v105, 16, v103
	v_mul_f32_e32 v106, v98, v99
	v_mul_f32_e32 v99, 0xbfb8aa3b, v105
	v_exp_f32_e32 v99, v99
	v_mul_f32_e32 v98, v108, v140
	v_mov_b32_e32 v104, v100
	v_and_b32_e32 v103, 0xffff0000, v103
	v_add_f32_e32 v99, 1.0, v99
	v_rcp_f32_e32 v99, v99
	s_nop 0
	v_pk_mul_f32 v[98:99], v[98:99], v[104:105]
	s_nop 0
	v_mul_f32_e32 v100, v98, v99
	v_mul_f32_e32 v99, 0xbfb8aa3b, v103
	v_exp_f32_e32 v99, v99
	v_mul_f32_e32 v98, v109, v140
	v_mul_f32_e32 v104, v110, v140
	v_add_f32_e32 v99, 1.0, v99
	v_rcp_f32_e32 v99, v99
	s_nop 0
	v_pk_mul_f32 v[98:99], v[98:99], v[102:103]
	s_nop 0
	v_mul_f32_e32 v99, v98, v99
	v_cvt_pk_bf16_f32 v98, v114, v106
	v_cvt_pk_bf16_f32 v99, v100, v99
	global_store_dwordx2 v[134:135], v[98:99], off offset:96
	global_load_dwordx2 v[102:103], v[134:135], off offset:112
	s_nop 0
	global_load_dwordx4 v[98:101], v[170:171], off offset:224
	s_waitcnt vmcnt(1)
	v_lshlrev_b32_e32 v107, 16, v102
	v_mul_f32_e32 v105, 0xbfb8aa3b, v107
	v_exp_f32_e32 v105, v105
	s_waitcnt vmcnt(0)
	v_mov_b32_e32 v106, v98
	v_add_f32_e32 v105, 1.0, v105
	v_rcp_f32_e32 v105, v105
	s_nop 0
	v_pk_mul_f32 v[104:105], v[104:105], v[106:107]
	v_and_b32_e32 v107, 0xffff0000, v102
	v_mul_f32_e32 v98, 0xbfb8aa3b, v107
	v_exp_f32_e32 v98, v98
	v_mul_f32_e32 v108, v104, v105
	v_mul_f32_e32 v104, v111, v140
	v_mov_b32_e32 v106, v99
	v_add_f32_e32 v98, 1.0, v98
	v_rcp_f32_e32 v105, v98
	v_mov_b32_e32 v102, v101
	v_pk_mul_f32 v[98:99], v[104:105], v[106:107]
	v_lshlrev_b32_e32 v105, 16, v103
	v_mul_f32_e32 v106, v98, v99
	v_mul_f32_e32 v99, 0xbfb8aa3b, v105
	v_exp_f32_e32 v99, v99
	v_mul_f32_e32 v98, v112, v140
	v_mov_b32_e32 v104, v100
	v_and_b32_e32 v103, 0xffff0000, v103
	v_add_f32_e32 v99, 1.0, v99
	v_rcp_f32_e32 v99, v99
	s_nop 0
	v_pk_mul_f32 v[98:99], v[98:99], v[104:105]
	s_nop 0
	v_mul_f32_e32 v100, v98, v99
	v_mul_f32_e32 v99, 0xbfb8aa3b, v103
	v_exp_f32_e32 v99, v99
	v_mul_f32_e32 v98, v113, v140
	v_mul_f32_e32 v104, v82, v140
	v_add_f32_e32 v99, 1.0, v99
	v_rcp_f32_e32 v99, v99
	s_nop 0
	v_pk_mul_f32 v[98:99], v[98:99], v[102:103]
	s_nop 0
	v_mul_f32_e32 v99, v98, v99
	v_cvt_pk_bf16_f32 v98, v108, v106
	v_cvt_pk_bf16_f32 v99, v100, v99
	global_store_dwordx2 v[134:135], v[98:99], off offset:112
	global_load_dwordx2 v[102:103], v[134:135], off offset:128
	s_nop 0
	global_load_dwordx4 v[98:101], v[170:171], off offset:256
	s_waitcnt vmcnt(1)
; __device__ __forceinline__ unsigned cvt_pk_bf16(float lo, float hi) { unsigned r; asm volatile("v_cvt_pk_bf16_f32 %0, %1, %2" : "=v"(r) : "v"(lo), "v"(hi)); return r; }
; __device__ __forceinline__ float bf_lo(unsigned w) { return __uint_as_float(w << 16); }
; __device__ __forceinline__ float bf_hi(unsigned w) { return __uint_as_float(w & 0xffff0000u); }
; __device__ __forceinline__ float siluf_(float v) { return v * sigmoidf_(v); }
; __device__ __forceinline__ void gla_out(const Params& p, LAS unsigned char* lds, int l) {
;     ...
;             bf16_t* zp = proj + (size_t)(tok0 + 32 * ib + r32) * NP + C_ZC + h * 256; const float* gn = p.gla_norm + l * 1024 + h * 256;
; #pragma unroll
;             for (int dvb = 0; dvb < 8; ++dvb)
; #pragma unroll
;                 for (int rq = 0; rq < 4; ++rq) { const int dv = dvb * 32 + 8 * rq + 4 * hi; const u32x2 zz = *(const u32x2*)(zp + dv); const f32x4 g4 = *(const f32x4*)(gn + dv);
;                     const float y0 = o[dvb][rq * 4 + 0] * rs * g4[0] * siluf_(bf_lo(zz.x)), y1 = o[dvb][rq * 4 + 1] * rs * g4[1] * siluf_(bf_hi(zz.x));
;                     const float y2 = o[dvb][rq * 4 + 2] * rs * g4[2] * siluf_(bf_lo(zz.y)), y3 = o[dvb][rq * 4 + 3] * rs * g4[3] * siluf_(bf_hi(zz.y));
;                     u32x2 w; w.x = cvt_pk_bf16(y0, y1); w.y = cvt_pk_bf16(y2, y3); *(u32x2*)(zp + dv) = w; }
	v_lshlrev_b32_e32 v107, 16, v102
	v_mul_f32_e32 v82, 0xbfb8aa3b, v107
	v_exp_f32_e32 v82, v82
	s_waitcnt vmcnt(0)
	v_mov_b32_e32 v106, v98
	v_mov_b32_e32 v98, v100
	v_mul_f32_e32 v100, v86, v140
	v_add_f32_e32 v82, 1.0, v82
	v_rcp_f32_e32 v105, v82
	v_mul_f32_e32 v82, v83, v140
	v_pk_mul_f32 v[104:105], v[104:105], v[106:107]
	s_nop 0
	v_mul_f32_e32 v106, v104, v105
	v_and_b32_e32 v105, 0xffff0000, v102
	v_mul_f32_e32 v83, 0xbfb8aa3b, v105
	v_exp_f32_e32 v83, v83
	v_mov_b32_e32 v104, v99
	v_lshlrev_b32_e32 v99, 16, v103
	v_add_f32_e32 v83, 1.0, v83
	v_rcp_f32_e32 v83, v83
	s_nop 0
	v_pk_mul_f32 v[82:83], v[82:83], v[104:105]
	s_nop 0
	v_mul_f32_e32 v102, v82, v83
	v_mul_f32_e32 v83, 0xbfb8aa3b, v99
	v_exp_f32_e32 v83, v83
	v_mul_f32_e32 v82, v84, v140
	v_mov_b32_e32 v84, v101
	v_add_f32_e32 v83, 1.0, v83
	v_rcp_f32_e32 v83, v83
	s_nop 0
	v_pk_mul_f32 v[82:83], v[82:83], v[98:99]
	s_nop 0
	v_mul_f32_e32 v98, v82, v83
	v_mul_f32_e32 v82, v85, v140
	v_and_b32_e32 v85, 0xffff0000, v103
	v_mul_f32_e32 v83, 0xbfb8aa3b, v85
	v_exp_f32_e32 v83, v83
	s_nop 0
	v_add_f32_e32 v83, 1.0, v83
	v_rcp_f32_e32 v83, v83
	s_nop 0
	v_pk_mul_f32 v[82:83], v[82:83], v[84:85]
	s_nop 0
	v_mul_f32_e32 v83, v82, v83
	v_cvt_pk_bf16_f32 v82, v106, v102
	v_cvt_pk_bf16_f32 v83, v98, v83
	global_store_dwordx2 v[134:135], v[82:83], off offset:128
	global_load_dwordx2 v[98:99], v[134:135], off offset:144
	s_nop 0
	global_load_dwordx4 v[82:85], v[170:171], off offset:288
	s_waitcnt vmcnt(1)
	v_lshlrev_b32_e32 v103, 16, v98
	v_mul_f32_e32 v86, 0xbfb8aa3b, v103
	v_exp_f32_e32 v86, v86
	s_waitcnt vmcnt(0)
	v_mov_b32_e32 v102, v82
	v_add_f32_e32 v86, 1.0, v86
	v_rcp_f32_e32 v101, v86
	v_mul_f32_e32 v86, v87, v140
	v_pk_mul_f32 v[100:101], v[100:101], v[102:103]
	s_nop 0
	v_mul_f32_e32 v102, v100, v101
	v_and_b32_e32 v101, 0xffff0000, v98
	v_mul_f32_e32 v82, 0xbfb8aa3b, v101
	v_exp_f32_e32 v82, v82
	v_mov_b32_e32 v100, v83
	v_add_f32_e32 v82, 1.0, v82
	v_rcp_f32_e32 v87, v82
	s_nop 0
	v_pk_mul_f32 v[82:83], v[86:87], v[100:101]
	v_lshlrev_b32_e32 v87, 16, v99
	v_mul_f32_e32 v98, v82, v83
	v_mul_f32_e32 v83, 0xbfb8aa3b, v87
	v_exp_f32_e32 v83, v83
	v_mul_f32_e32 v82, v88, v140
	v_mov_b32_e32 v86, v84
	v_mul_f32_e32 v88, v90, v140
	v_add_f32_e32 v83, 1.0, v83
	v_rcp_f32_e32 v83, v83
	s_nop 0
	v_pk_mul_f32 v[82:83], v[82:83], v[86:87]
	v_and_b32_e32 v87, 0xffff0000, v99
	v_mul_f32_e32 v84, v82, v83
	v_mul_f32_e32 v83, 0xbfb8aa3b, v87
	v_exp_f32_e32 v83, v83
	v_mul_f32_e32 v82, v89, v140
	v_mov_b32_e32 v86, v85
	v_add_f32_e32 v83, 1.0, v83
	v_rcp_f32_e32 v83, v83
	s_nop 0
	v_pk_mul_f32 v[82:83], v[82:83], v[86:87]
	s_nop 0
	v_mul_f32_e32 v83, v82, v83
	v_cvt_pk_bf16_f32 v82, v102, v98
	v_cvt_pk_bf16_f32 v83, v84, v83
	global_store_dwordx2 v[134:135], v[82:83], off offset:144
	global_load_dwordx2 v[86:87], v[134:135], off offset:160
	s_nop 0
	global_load_dwordx4 v[82:85], v[170:171], off offset:320
	s_waitcnt vmcnt(1)
	v_lshlrev_b32_e32 v99, 16, v86
	v_mul_f32_e32 v89, 0xbfb8aa3b, v99
	v_exp_f32_e32 v89, v89
	s_waitcnt vmcnt(0)
	v_mov_b32_e32 v98, v82
	v_mov_b32_e32 v90, v83
	v_add_f32_e32 v89, 1.0, v89
	v_rcp_f32_e32 v89, v89
	s_nop 0
	v_pk_mul_f32 v[88:89], v[88:89], v[98:99]
	s_nop 0
	v_mul_f32_e32 v98, v88, v89
	v_mul_f32_e32 v88, v91, v140
	v_and_b32_e32 v91, 0xffff0000, v86
	v_mul_f32_e32 v82, 0xbfb8aa3b, v91
	v_exp_f32_e32 v82, v82
	v_mov_b32_e32 v86, v85
	v_add_f32_e32 v82, 1.0, v82
	v_rcp_f32_e32 v89, v82
	s_nop 0
	v_pk_mul_f32 v[82:83], v[88:89], v[90:91]
	v_lshlrev_b32_e32 v89, 16, v87
	v_mul_f32_e32 v90, v82, v83
	v_mul_f32_e32 v83, 0xbfb8aa3b, v89
	v_exp_f32_e32 v83, v83
	v_mul_f32_e32 v82, v92, v140
	v_mov_b32_e32 v88, v84
	v_and_b32_e32 v87, 0xffff0000, v87
	v_add_f32_e32 v83, 1.0, v83
	v_rcp_f32_e32 v83, v83
	s_nop 0
	v_pk_mul_f32 v[82:83], v[82:83], v[88:89]
	s_nop 0
	v_mul_f32_e32 v84, v82, v83
	v_mul_f32_e32 v83, 0xbfb8aa3b, v87
	v_exp_f32_e32 v83, v83
	v_mul_f32_e32 v82, v93, v140
	v_mul_f32_e32 v88, v94, v140
	v_add_f32_e32 v83, 1.0, v83
	v_rcp_f32_e32 v83, v83
	s_nop 0
	v_pk_mul_f32 v[82:83], v[82:83], v[86:87]
	s_nop 0
	v_mul_f32_e32 v83, v82, v83
	v_cvt_pk_bf16_f32 v82, v98, v90
	v_cvt_pk_bf16_f32 v83, v84, v83
	global_store_dwordx2 v[134:135], v[82:83], off offset:160
	global_load_dwordx2 v[86:87], v[134:135], off offset:176
	s_nop 0
	global_load_dwordx4 v[82:85], v[170:171], off offset:352
	s_waitcnt vmcnt(1)
	v_lshlrev_b32_e32 v91, 16, v86
	v_mul_f32_e32 v89, 0xbfb8aa3b, v91
	v_exp_f32_e32 v89, v89
	s_waitcnt vmcnt(0)
	v_mov_b32_e32 v90, v82
	v_add_f32_e32 v89, 1.0, v89
	v_rcp_f32_e32 v89, v89
	s_nop 0
	v_pk_mul_f32 v[88:89], v[88:89], v[90:91]
	v_and_b32_e32 v91, 0xffff0000, v86
	v_mul_f32_e32 v82, 0xbfb8aa3b, v91
	v_exp_f32_e32 v82, v82
	v_mul_f32_e32 v92, v88, v89
	v_mul_f32_e32 v88, v95, v140
	v_mov_b32_e32 v90, v83
	v_add_f32_e32 v82, 1.0, v82
	v_rcp_f32_e32 v89, v82
	v_mov_b32_e32 v86, v85
	v_pk_mul_f32 v[82:83], v[88:89], v[90:91]
	v_lshlrev_b32_e32 v89, 16, v87
	v_mul_f32_e32 v90, v82, v83
	v_mul_f32_e32 v83, 0xbfb8aa3b, v89
	v_exp_f32_e32 v83, v83
	v_mul_f32_e32 v82, v96, v140
	v_mov_b32_e32 v88, v84
	v_and_b32_e32 v87, 0xffff0000, v87
	v_add_f32_e32 v83, 1.0, v83
	v_rcp_f32_e32 v83, v83
	s_nop 0
	v_pk_mul_f32 v[82:83], v[82:83], v[88:89]
	s_nop 0
	v_mul_f32_e32 v84, v82, v83
	v_mul_f32_e32 v83, 0xbfb8aa3b, v87
	v_exp_f32_e32 v83, v83
	v_mul_f32_e32 v82, v97, v140
	v_mul_f32_e32 v88, v66, v140
	v_add_f32_e32 v83, 1.0, v83
	v_rcp_f32_e32 v83, v83
	s_nop 0
	v_pk_mul_f32 v[82:83], v[82:83], v[86:87]
	s_nop 0
	v_mul_f32_e32 v83, v82, v83
	v_cvt_pk_bf16_f32 v82, v92, v90
	v_cvt_pk_bf16_f32 v83, v84, v83
	global_store_dwordx2 v[134:135], v[82:83], off offset:176
	global_load_dwordx2 v[86:87], v[134:135], off offset:192
	s_nop 0
	global_load_dwordx4 v[82:85], v[170:171], off offset:384
	s_waitcnt vmcnt(1)
; __device__ __forceinline__ unsigned cvt_pk_bf16(float lo, float hi) { unsigned r; asm volatile("v_cvt_pk_bf16_f32 %0, %1, %2" : "=v"(r) : "v"(lo), "v"(hi)); return r; }
; __device__ __forceinline__ float bf_lo(unsigned w) { return __uint_as_float(w << 16); }
; __device__ __forceinline__ float bf_hi(unsigned w) { return __uint_as_float(w & 0xffff0000u); }
; __device__ __forceinline__ float siluf_(float v) { return v * sigmoidf_(v); }
; __device__ __forceinline__ void gla_out(const Params& p, LAS unsigned char* lds, int l) {
;     ...
;             bf16_t* zp = proj + (size_t)(tok0 + 32 * ib + r32) * NP + C_ZC + h * 256; const float* gn = p.gla_norm + l * 1024 + h * 256;
; #pragma unroll
;             for (int dvb = 0; dvb < 8; ++dvb)
; #pragma unroll
;                 for (int rq = 0; rq < 4; ++rq) { const int dv = dvb * 32 + 8 * rq + 4 * hi; const u32x2 zz = *(const u32x2*)(zp + dv); const f32x4 g4 = *(const f32x4*)(gn + dv);
;                     const float y0 = o[dvb][rq * 4 + 0] * rs * g4[0] * siluf_(bf_lo(zz.x)), y1 = o[dvb][rq * 4 + 1] * rs * g4[1] * siluf_(bf_hi(zz.x));
;                     const float y2 = o[dvb][rq * 4 + 2] * rs * g4[2] * siluf_(bf_lo(zz.y)), y3 = o[dvb][rq * 4 + 3] * rs * g4[3] * siluf_(bf_hi(zz.y));
;                     u32x2 w; w.x = cvt_pk_bf16(y0, y1); w.y = cvt_pk_bf16(y2, y3); *(u32x2*)(zp + dv) = w; }
	v_lshlrev_b32_e32 v91, 16, v86
	v_mul_f32_e32 v66, 0xbfb8aa3b, v91
	v_exp_f32_e32 v66, v66
	s_waitcnt vmcnt(0)
	v_mov_b32_e32 v90, v82
	v_mov_b32_e32 v82, v84
	v_mul_f32_e32 v84, v70, v140
	v_add_f32_e32 v66, 1.0, v66
	v_rcp_f32_e32 v89, v66
	v_mul_f32_e32 v66, v67, v140
	v_pk_mul_f32 v[88:89], v[88:89], v[90:91]
	s_nop 0
	v_mul_f32_e32 v90, v88, v89
	v_and_b32_e32 v89, 0xffff0000, v86
	v_mul_f32_e32 v67, 0xbfb8aa3b, v89
	v_exp_f32_e32 v67, v67
	v_mov_b32_e32 v88, v83
	v_lshlrev_b32_e32 v83, 16, v87
	v_add_f32_e32 v67, 1.0, v67
	v_rcp_f32_e32 v67, v67
	s_nop 0
	v_pk_mul_f32 v[66:67], v[66:67], v[88:89]
	s_nop 0
	v_mul_f32_e32 v86, v66, v67
	v_mul_f32_e32 v67, 0xbfb8aa3b, v83
	v_exp_f32_e32 v67, v67
	v_mul_f32_e32 v66, v68, v140
	v_mov_b32_e32 v68, v85
	v_add_f32_e32 v67, 1.0, v67
	v_rcp_f32_e32 v67, v67
	s_nop 0
	v_pk_mul_f32 v[66:67], v[66:67], v[82:83]
	s_nop 0
	v_mul_f32_e32 v82, v66, v67
	v_mul_f32_e32 v66, v69, v140
	v_and_b32_e32 v69, 0xffff0000, v87
	v_mul_f32_e32 v67, 0xbfb8aa3b, v69
	v_exp_f32_e32 v67, v67
	s_nop 0
	v_add_f32_e32 v67, 1.0, v67
	v_rcp_f32_e32 v67, v67
	s_nop 0
	v_pk_mul_f32 v[66:67], v[66:67], v[68:69]
	s_nop 0
	v_mul_f32_e32 v67, v66, v67
	v_cvt_pk_bf16_f32 v66, v90, v86
	v_cvt_pk_bf16_f32 v67, v82, v67
	global_store_dwordx2 v[134:135], v[66:67], off offset:192
	global_load_dwordx2 v[82:83], v[134:135], off offset:208
	s_nop 0
	global_load_dwordx4 v[66:69], v[170:171], off offset:416
	s_waitcnt vmcnt(1)
	v_lshlrev_b32_e32 v87, 16, v82
	v_mul_f32_e32 v70, 0xbfb8aa3b, v87
	v_exp_f32_e32 v70, v70
	s_waitcnt vmcnt(0)
	v_mov_b32_e32 v86, v66
	v_add_f32_e32 v70, 1.0, v70
	v_rcp_f32_e32 v85, v70
	v_mul_f32_e32 v70, v71, v140
	v_pk_mul_f32 v[84:85], v[84:85], v[86:87]
	s_nop 0
	v_mul_f32_e32 v86, v84, v85
	v_and_b32_e32 v85, 0xffff0000, v82
	v_mul_f32_e32 v66, 0xbfb8aa3b, v85
	v_exp_f32_e32 v66, v66
	v_mov_b32_e32 v84, v67
	v_add_f32_e32 v66, 1.0, v66
	v_rcp_f32_e32 v71, v66
	s_nop 0
	v_pk_mul_f32 v[66:67], v[70:71], v[84:85]
	v_lshlrev_b32_e32 v71, 16, v83
	v_mul_f32_e32 v82, v66, v67
	v_mul_f32_e32 v67, 0xbfb8aa3b, v71
	v_exp_f32_e32 v67, v67
	v_mul_f32_e32 v66, v72, v140
	v_mov_b32_e32 v70, v68
	v_mul_f32_e32 v72, v74, v140
	v_add_f32_e32 v67, 1.0, v67
	v_rcp_f32_e32 v67, v67
	s_nop 0
	v_pk_mul_f32 v[66:67], v[66:67], v[70:71]
	v_and_b32_e32 v71, 0xffff0000, v83
	v_mul_f32_e32 v68, v66, v67
	v_mul_f32_e32 v67, 0xbfb8aa3b, v71
	v_exp_f32_e32 v67, v67
	v_mul_f32_e32 v66, v73, v140
	v_mov_b32_e32 v70, v69
	v_add_f32_e32 v67, 1.0, v67
	v_rcp_f32_e32 v67, v67
	s_nop 0
	v_pk_mul_f32 v[66:67], v[66:67], v[70:71]
	s_nop 0
	v_mul_f32_e32 v67, v66, v67
	v_cvt_pk_bf16_f32 v66, v86, v82
	v_cvt_pk_bf16_f32 v67, v68, v67
	global_store_dwordx2 v[134:135], v[66:67], off offset:208
	global_load_dwordx2 v[70:71], v[134:135], off offset:224
	s_nop 0
	global_load_dwordx4 v[66:69], v[170:171], off offset:448
	s_waitcnt vmcnt(1)
	v_lshlrev_b32_e32 v83, 16, v70
	v_mul_f32_e32 v73, 0xbfb8aa3b, v83
	v_exp_f32_e32 v73, v73
	s_waitcnt vmcnt(0)
	v_mov_b32_e32 v82, v66
	v_mov_b32_e32 v74, v67
	v_add_f32_e32 v73, 1.0, v73
	v_rcp_f32_e32 v73, v73
	s_nop 0
	v_pk_mul_f32 v[72:73], v[72:73], v[82:83]
	s_nop 0
	v_mul_f32_e32 v82, v72, v73
	v_mul_f32_e32 v72, v75, v140
	v_and_b32_e32 v75, 0xffff0000, v70
	v_mul_f32_e32 v66, 0xbfb8aa3b, v75
	v_exp_f32_e32 v66, v66
	v_mov_b32_e32 v70, v69
	v_add_f32_e32 v66, 1.0, v66
	v_rcp_f32_e32 v73, v66
	s_nop 0
	v_pk_mul_f32 v[66:67], v[72:73], v[74:75]
	v_lshlrev_b32_e32 v73, 16, v71
	v_mul_f32_e32 v74, v66, v67
	v_mul_f32_e32 v67, 0xbfb8aa3b, v73
	v_exp_f32_e32 v67, v67
	v_mul_f32_e32 v66, v76, v140
	v_mov_b32_e32 v72, v68
	v_and_b32_e32 v71, 0xffff0000, v71
	v_add_f32_e32 v67, 1.0, v67
	v_rcp_f32_e32 v67, v67
	s_nop 0
	v_pk_mul_f32 v[66:67], v[66:67], v[72:73]
	s_nop 0
	v_mul_f32_e32 v68, v66, v67
	v_mul_f32_e32 v67, 0xbfb8aa3b, v71
	v_exp_f32_e32 v67, v67
	v_mul_f32_e32 v66, v77, v140
	v_mul_f32_e32 v72, v78, v140
	v_add_f32_e32 v67, 1.0, v67
	v_rcp_f32_e32 v67, v67
	s_nop 0
	v_pk_mul_f32 v[66:67], v[66:67], v[70:71]
	s_nop 0
	v_mul_f32_e32 v67, v66, v67
	v_cvt_pk_bf16_f32 v66, v82, v74
	v_cvt_pk_bf16_f32 v67, v68, v67
	global_store_dwordx2 v[134:135], v[66:67], off offset:224
	global_load_dwordx2 v[70:71], v[134:135], off offset:240
	s_nop 0
	global_load_dwordx4 v[66:69], v[170:171], off offset:480
	s_waitcnt vmcnt(1)
	v_lshlrev_b32_e32 v75, 16, v70
	v_mul_f32_e32 v73, 0xbfb8aa3b, v75
	v_exp_f32_e32 v73, v73
	s_waitcnt vmcnt(0)
	v_mov_b32_e32 v74, v66
	v_add_f32_e32 v73, 1.0, v73
	v_rcp_f32_e32 v73, v73
	s_nop 0
	v_pk_mul_f32 v[72:73], v[72:73], v[74:75]
	v_and_b32_e32 v75, 0xffff0000, v70
	v_mul_f32_e32 v66, 0xbfb8aa3b, v75
	v_exp_f32_e32 v66, v66
	v_mul_f32_e32 v76, v72, v73
	v_mul_f32_e32 v72, v79, v140
	v_mov_b32_e32 v74, v67
	v_add_f32_e32 v66, 1.0, v66
	v_rcp_f32_e32 v73, v66
	v_mov_b32_e32 v70, v69
	v_pk_mul_f32 v[66:67], v[72:73], v[74:75]
	v_lshlrev_b32_e32 v73, 16, v71
	v_mul_f32_e32 v74, v66, v67
	v_mul_f32_e32 v67, 0xbfb8aa3b, v73
	v_exp_f32_e32 v67, v67
	v_mul_f32_e32 v66, v80, v140
	v_mov_b32_e32 v72, v68
	v_and_b32_e32 v71, 0xffff0000, v71
	v_add_f32_e32 v67, 1.0, v67
	v_rcp_f32_e32 v67, v67
	s_nop 0
	v_pk_mul_f32 v[66:67], v[66:67], v[72:73]
	s_nop 0
	v_mul_f32_e32 v68, v66, v67
	v_mul_f32_e32 v67, 0xbfb8aa3b, v71
	v_exp_f32_e32 v67, v67
	v_mul_f32_e32 v66, v81, v140
	v_mul_f32_e32 v72, v50, v140
	v_add_f32_e32 v67, 1.0, v67
	v_rcp_f32_e32 v67, v67
	s_nop 0
	v_pk_mul_f32 v[66:67], v[66:67], v[70:71]
	s_nop 0
	v_mul_f32_e32 v67, v66, v67
	v_cvt_pk_bf16_f32 v66, v76, v74
	v_cvt_pk_bf16_f32 v67, v68, v67
	global_store_dwordx2 v[134:135], v[66:67], off offset:240
	global_load_dwordx2 v[70:71], v[134:135], off offset:256
	s_nop 0
	global_load_dwordx4 v[66:69], v[170:171], off offset:512
	s_waitcnt vmcnt(1)
; __device__ __forceinline__ unsigned cvt_pk_bf16(float lo, float hi) { unsigned r; asm volatile("v_cvt_pk_bf16_f32 %0, %1, %2" : "=v"(r) : "v"(lo), "v"(hi)); return r; }
; __device__ __forceinline__ float bf_lo(unsigned w) { return __uint_as_float(w << 16); }
; __device__ __forceinline__ float bf_hi(unsigned w) { return __uint_as_float(w & 0xffff0000u); }
; __device__ __forceinline__ float siluf_(float v) { return v * sigmoidf_(v); }
; __device__ __forceinline__ void gla_out(const Params& p, LAS unsigned char* lds, int l) {
;     ...
;             bf16_t* zp = proj + (size_t)(tok0 + 32 * ib + r32) * NP + C_ZC + h * 256; const float* gn = p.gla_norm + l * 1024 + h * 256;
; #pragma unroll
;             for (int dvb = 0; dvb < 8; ++dvb)
; #pragma unroll
;                 for (int rq = 0; rq < 4; ++rq) { const int dv = dvb * 32 + 8 * rq + 4 * hi; const u32x2 zz = *(const u32x2*)(zp + dv); const f32x4 g4 = *(const f32x4*)(gn + dv);
;                     const float y0 = o[dvb][rq * 4 + 0] * rs * g4[0] * siluf_(bf_lo(zz.x)), y1 = o[dvb][rq * 4 + 1] * rs * g4[1] * siluf_(bf_hi(zz.x));
;                     const float y2 = o[dvb][rq * 4 + 2] * rs * g4[2] * siluf_(bf_lo(zz.y)), y3 = o[dvb][rq * 4 + 3] * rs * g4[3] * siluf_(bf_hi(zz.y));
;                     u32x2 w; w.x = cvt_pk_bf16(y0, y1); w.y = cvt_pk_bf16(y2, y3); *(u32x2*)(zp + dv) = w; }
	v_lshlrev_b32_e32 v75, 16, v70
	v_mul_f32_e32 v50, 0xbfb8aa3b, v75
	v_exp_f32_e32 v50, v50
	s_waitcnt vmcnt(0)
	v_mov_b32_e32 v74, v66
	v_mov_b32_e32 v66, v68
	v_mul_f32_e32 v68, v54, v140
	v_add_f32_e32 v50, 1.0, v50
	v_rcp_f32_e32 v73, v50
	v_mul_f32_e32 v50, v51, v140
	v_pk_mul_f32 v[72:73], v[72:73], v[74:75]
	s_nop 0
	v_mul_f32_e32 v74, v72, v73
	v_and_b32_e32 v73, 0xffff0000, v70
	v_mul_f32_e32 v51, 0xbfb8aa3b, v73
	v_exp_f32_e32 v51, v51
	v_mov_b32_e32 v72, v67
	v_lshlrev_b32_e32 v67, 16, v71
	v_add_f32_e32 v51, 1.0, v51
	v_rcp_f32_e32 v51, v51
	s_nop 0
	v_pk_mul_f32 v[50:51], v[50:51], v[72:73]
	s_nop 0
	v_mul_f32_e32 v70, v50, v51
	v_mul_f32_e32 v51, 0xbfb8aa3b, v67
	v_exp_f32_e32 v51, v51
	v_mul_f32_e32 v50, v52, v140
	v_mov_b32_e32 v52, v69
	v_add_f32_e32 v51, 1.0, v51
	v_rcp_f32_e32 v51, v51
	s_nop 0
	v_pk_mul_f32 v[50:51], v[50:51], v[66:67]
	s_nop 0
	v_mul_f32_e32 v66, v50, v51
	v_mul_f32_e32 v50, v53, v140
	v_and_b32_e32 v53, 0xffff0000, v71
	v_mul_f32_e32 v51, 0xbfb8aa3b, v53
	v_exp_f32_e32 v51, v51
	s_nop 0
	v_add_f32_e32 v51, 1.0, v51
	v_rcp_f32_e32 v51, v51
	s_nop 0
	v_pk_mul_f32 v[50:51], v[50:51], v[52:53]
	s_nop 0
	v_mul_f32_e32 v51, v50, v51
	v_cvt_pk_bf16_f32 v50, v74, v70
	v_cvt_pk_bf16_f32 v51, v66, v51
	global_store_dwordx2 v[134:135], v[50:51], off offset:256
	global_load_dwordx2 v[66:67], v[134:135], off offset:272
	s_nop 0
	global_load_dwordx4 v[50:53], v[170:171], off offset:544
	s_waitcnt vmcnt(1)
	v_lshlrev_b32_e32 v71, 16, v66
	v_mul_f32_e32 v54, 0xbfb8aa3b, v71
	v_exp_f32_e32 v54, v54
	s_waitcnt vmcnt(0)
	v_mov_b32_e32 v70, v50
	v_add_f32_e32 v54, 1.0, v54
	v_rcp_f32_e32 v69, v54
	v_mul_f32_e32 v54, v55, v140
	v_pk_mul_f32 v[68:69], v[68:69], v[70:71]
	s_nop 0
	v_mul_f32_e32 v70, v68, v69
	v_and_b32_e32 v69, 0xffff0000, v66
	v_mul_f32_e32 v50, 0xbfb8aa3b, v69
	v_exp_f32_e32 v50, v50
	v_mov_b32_e32 v68, v51
	v_add_f32_e32 v50, 1.0, v50
	v_rcp_f32_e32 v55, v50
	s_nop 0
	v_pk_mul_f32 v[50:51], v[54:55], v[68:69]
	v_lshlrev_b32_e32 v55, 16, v67
	v_mul_f32_e32 v66, v50, v51
	v_mul_f32_e32 v51, 0xbfb8aa3b, v55
	v_exp_f32_e32 v51, v51
	v_mul_f32_e32 v50, v56, v140
	v_mov_b32_e32 v54, v52
	v_mul_f32_e32 v56, v58, v140
	v_add_f32_e32 v51, 1.0, v51
	v_rcp_f32_e32 v51, v51
	s_nop 0
	v_pk_mul_f32 v[50:51], v[50:51], v[54:55]
	v_and_b32_e32 v55, 0xffff0000, v67
	v_mul_f32_e32 v52, v50, v51
	v_mul_f32_e32 v51, 0xbfb8aa3b, v55
	v_exp_f32_e32 v51, v51
	v_mul_f32_e32 v50, v57, v140
	v_mov_b32_e32 v54, v53
	v_add_f32_e32 v51, 1.0, v51
	v_rcp_f32_e32 v51, v51
	s_nop 0
	v_pk_mul_f32 v[50:51], v[50:51], v[54:55]
	s_nop 0
	v_mul_f32_e32 v51, v50, v51
	v_cvt_pk_bf16_f32 v50, v70, v66
	v_cvt_pk_bf16_f32 v51, v52, v51
	global_store_dwordx2 v[134:135], v[50:51], off offset:272
	global_load_dwordx2 v[54:55], v[134:135], off offset:288
	s_nop 0
	global_load_dwordx4 v[50:53], v[170:171], off offset:576
	s_waitcnt vmcnt(1)
	v_lshlrev_b32_e32 v67, 16, v54
	v_mul_f32_e32 v57, 0xbfb8aa3b, v67
	v_exp_f32_e32 v57, v57
	s_waitcnt vmcnt(0)
	v_mov_b32_e32 v66, v50
	v_mov_b32_e32 v58, v51
	v_add_f32_e32 v57, 1.0, v57
	v_rcp_f32_e32 v57, v57
	s_nop 0
	v_pk_mul_f32 v[56:57], v[56:57], v[66:67]
	s_nop 0
	v_mul_f32_e32 v66, v56, v57
	v_mul_f32_e32 v56, v59, v140
	v_and_b32_e32 v59, 0xffff0000, v54
	v_mul_f32_e32 v50, 0xbfb8aa3b, v59
	v_exp_f32_e32 v50, v50
	v_mov_b32_e32 v54, v53
	v_add_f32_e32 v50, 1.0, v50
	v_rcp_f32_e32 v57, v50
	s_nop 0
	v_pk_mul_f32 v[50:51], v[56:57], v[58:59]
	v_lshlrev_b32_e32 v57, 16, v55
	v_mul_f32_e32 v58, v50, v51
	v_mul_f32_e32 v51, 0xbfb8aa3b, v57
	v_exp_f32_e32 v51, v51
	v_mul_f32_e32 v50, v60, v140
	v_mov_b32_e32 v56, v52
	v_and_b32_e32 v55, 0xffff0000, v55
	v_add_f32_e32 v51, 1.0, v51
	v_rcp_f32_e32 v51, v51
	s_nop 0
	v_pk_mul_f32 v[50:51], v[50:51], v[56:57]
	s_nop 0
	v_mul_f32_e32 v52, v50, v51
	v_mul_f32_e32 v51, 0xbfb8aa3b, v55
	v_exp_f32_e32 v51, v51
	v_mul_f32_e32 v50, v61, v140
	v_mul_f32_e32 v56, v62, v140
	v_add_f32_e32 v51, 1.0, v51
	v_rcp_f32_e32 v51, v51
	s_nop 0
	v_pk_mul_f32 v[50:51], v[50:51], v[54:55]
	s_nop 0
	v_mul_f32_e32 v51, v50, v51
	v_cvt_pk_bf16_f32 v50, v66, v58
	v_cvt_pk_bf16_f32 v51, v52, v51
	global_store_dwordx2 v[134:135], v[50:51], off offset:288
	global_load_dwordx2 v[54:55], v[134:135], off offset:304
	s_nop 0
	global_load_dwordx4 v[50:53], v[170:171], off offset:608
	s_waitcnt vmcnt(1)
	v_lshlrev_b32_e32 v59, 16, v54
	v_mul_f32_e32 v57, 0xbfb8aa3b, v59
	v_exp_f32_e32 v57, v57
	s_waitcnt vmcnt(0)
	v_mov_b32_e32 v58, v50
	v_add_f32_e32 v57, 1.0, v57
	v_rcp_f32_e32 v57, v57
	s_nop 0
	v_pk_mul_f32 v[56:57], v[56:57], v[58:59]
	v_and_b32_e32 v59, 0xffff0000, v54
	v_mul_f32_e32 v50, 0xbfb8aa3b, v59
	v_exp_f32_e32 v50, v50
	v_mul_f32_e32 v60, v56, v57
	v_mul_f32_e32 v56, v63, v140
	v_mov_b32_e32 v58, v51
	v_add_f32_e32 v50, 1.0, v50
	v_rcp_f32_e32 v57, v50
	v_mov_b32_e32 v54, v53
	v_pk_mul_f32 v[50:51], v[56:57], v[58:59]
	v_lshlrev_b32_e32 v57, 16, v55
	v_mul_f32_e32 v58, v50, v51
	v_mul_f32_e32 v51, 0xbfb8aa3b, v57
	v_exp_f32_e32 v51, v51
	v_mul_f32_e32 v50, v64, v140
	v_mov_b32_e32 v56, v52
	v_and_b32_e32 v55, 0xffff0000, v55
	v_add_f32_e32 v51, 1.0, v51
	v_rcp_f32_e32 v51, v51
	s_nop 0
	v_pk_mul_f32 v[50:51], v[50:51], v[56:57]
	s_nop 0
	v_mul_f32_e32 v52, v50, v51
	v_mul_f32_e32 v51, 0xbfb8aa3b, v55
	v_exp_f32_e32 v51, v51
	v_mul_f32_e32 v50, v65, v140
	v_mul_f32_e32 v56, v34, v140
	v_add_f32_e32 v51, 1.0, v51
	v_rcp_f32_e32 v51, v51
	s_nop 0
	v_pk_mul_f32 v[50:51], v[50:51], v[54:55]
	s_nop 0
	v_mul_f32_e32 v51, v50, v51
	v_cvt_pk_bf16_f32 v50, v60, v58
	v_cvt_pk_bf16_f32 v51, v52, v51
	global_store_dwordx2 v[134:135], v[50:51], off offset:304
	global_load_dwordx2 v[54:55], v[134:135], off offset:320
	s_nop 0
	global_load_dwordx4 v[50:53], v[170:171], off offset:640
	s_waitcnt vmcnt(1)
; __device__ __forceinline__ unsigned cvt_pk_bf16(float lo, float hi) { unsigned r; asm volatile("v_cvt_pk_bf16_f32 %0, %1, %2" : "=v"(r) : "v"(lo), "v"(hi)); return r; }
; __device__ __forceinline__ float bf_lo(unsigned w) { return __uint_as_float(w << 16); }
; __device__ __forceinline__ float bf_hi(unsigned w) { return __uint_as_float(w & 0xffff0000u); }
; __device__ __forceinline__ float siluf_(float v) { return v * sigmoidf_(v); }
; __device__ __forceinline__ void gla_out(const Params& p, LAS unsigned char* lds, int l) {
;     ...
;             bf16_t* zp = proj + (size_t)(tok0 + 32 * ib + r32) * NP + C_ZC + h * 256; const float* gn = p.gla_norm + l * 1024 + h * 256;
; #pragma unroll
;             for (int dvb = 0; dvb < 8; ++dvb)
; #pragma unroll
;                 for (int rq = 0; rq < 4; ++rq) { const int dv = dvb * 32 + 8 * rq + 4 * hi; const u32x2 zz = *(const u32x2*)(zp + dv); const f32x4 g4 = *(const f32x4*)(gn + dv);
;                     const float y0 = o[dvb][rq * 4 + 0] * rs * g4[0] * siluf_(bf_lo(zz.x)), y1 = o[dvb][rq * 4 + 1] * rs * g4[1] * siluf_(bf_hi(zz.x));
;                     const float y2 = o[dvb][rq * 4 + 2] * rs * g4[2] * siluf_(bf_lo(zz.y)), y3 = o[dvb][rq * 4 + 3] * rs * g4[3] * siluf_(bf_hi(zz.y));
;                     u32x2 w; w.x = cvt_pk_bf16(y0, y1); w.y = cvt_pk_bf16(y2, y3); *(u32x2*)(zp + dv) = w; }
	v_lshlrev_b32_e32 v59, 16, v54
	v_mul_f32_e32 v34, 0xbfb8aa3b, v59
	v_exp_f32_e32 v34, v34
	s_waitcnt vmcnt(0)
	v_mov_b32_e32 v58, v50
	v_mov_b32_e32 v50, v52
	v_mul_f32_e32 v52, v38, v140
	v_add_f32_e32 v34, 1.0, v34
	v_rcp_f32_e32 v57, v34
	v_mul_f32_e32 v34, v35, v140
	v_pk_mul_f32 v[56:57], v[56:57], v[58:59]
	s_nop 0
	v_mul_f32_e32 v58, v56, v57
	v_and_b32_e32 v57, 0xffff0000, v54
	v_mul_f32_e32 v35, 0xbfb8aa3b, v57
	v_exp_f32_e32 v35, v35
	v_mov_b32_e32 v56, v51
	v_lshlrev_b32_e32 v51, 16, v55
	v_add_f32_e32 v35, 1.0, v35
	v_rcp_f32_e32 v35, v35
	s_nop 0
	v_pk_mul_f32 v[34:35], v[34:35], v[56:57]
	s_nop 0
	v_mul_f32_e32 v54, v34, v35
	v_mul_f32_e32 v35, 0xbfb8aa3b, v51
	v_exp_f32_e32 v35, v35
	v_mul_f32_e32 v34, v36, v140
	v_mov_b32_e32 v36, v53
	v_add_f32_e32 v35, 1.0, v35
	v_rcp_f32_e32 v35, v35
	s_nop 0
	v_pk_mul_f32 v[34:35], v[34:35], v[50:51]
	s_nop 0
	v_mul_f32_e32 v50, v34, v35
	v_mul_f32_e32 v34, v37, v140
	v_and_b32_e32 v37, 0xffff0000, v55
	v_mul_f32_e32 v35, 0xbfb8aa3b, v37
	v_exp_f32_e32 v35, v35
	s_nop 0
	v_add_f32_e32 v35, 1.0, v35
	v_rcp_f32_e32 v35, v35
	s_nop 0
	v_pk_mul_f32 v[34:35], v[34:35], v[36:37]
	s_nop 0
	v_mul_f32_e32 v35, v34, v35
	v_cvt_pk_bf16_f32 v34, v58, v54
	v_cvt_pk_bf16_f32 v35, v50, v35
	global_store_dwordx2 v[134:135], v[34:35], off offset:320
	global_load_dwordx2 v[50:51], v[134:135], off offset:336
	s_nop 0
	global_load_dwordx4 v[34:37], v[170:171], off offset:672
	s_waitcnt vmcnt(1)
	v_lshlrev_b32_e32 v55, 16, v50
	v_mul_f32_e32 v38, 0xbfb8aa3b, v55
	v_exp_f32_e32 v38, v38
	s_waitcnt vmcnt(0)
	v_mov_b32_e32 v54, v34
	v_add_f32_e32 v38, 1.0, v38
	v_rcp_f32_e32 v53, v38
	v_mul_f32_e32 v38, v39, v140
	v_pk_mul_f32 v[52:53], v[52:53], v[54:55]
	s_nop 0
	v_mul_f32_e32 v54, v52, v53
	v_and_b32_e32 v53, 0xffff0000, v50
	v_mul_f32_e32 v34, 0xbfb8aa3b, v53
	v_exp_f32_e32 v34, v34
	v_mov_b32_e32 v52, v35
	v_add_f32_e32 v34, 1.0, v34
	v_rcp_f32_e32 v39, v34
	s_nop 0
	v_pk_mul_f32 v[34:35], v[38:39], v[52:53]
	v_lshlrev_b32_e32 v39, 16, v51
	v_mul_f32_e32 v50, v34, v35
	v_mul_f32_e32 v35, 0xbfb8aa3b, v39
	v_exp_f32_e32 v35, v35
	v_mul_f32_e32 v34, v40, v140
	v_mov_b32_e32 v38, v36
	v_mul_f32_e32 v40, v42, v140
	v_add_f32_e32 v35, 1.0, v35
	v_rcp_f32_e32 v35, v35
	s_nop 0
	v_pk_mul_f32 v[34:35], v[34:35], v[38:39]
	v_and_b32_e32 v39, 0xffff0000, v51
	v_mul_f32_e32 v36, v34, v35
	v_mul_f32_e32 v35, 0xbfb8aa3b, v39
	v_exp_f32_e32 v35, v35
	v_mul_f32_e32 v34, v41, v140
	v_mov_b32_e32 v38, v37
	v_add_f32_e32 v35, 1.0, v35
	v_rcp_f32_e32 v35, v35
	s_nop 0
	v_pk_mul_f32 v[34:35], v[34:35], v[38:39]
	s_nop 0
	v_mul_f32_e32 v35, v34, v35
	v_cvt_pk_bf16_f32 v34, v54, v50
	v_cvt_pk_bf16_f32 v35, v36, v35
	global_store_dwordx2 v[134:135], v[34:35], off offset:336
	global_load_dwordx2 v[38:39], v[134:135], off offset:352
	s_nop 0
	global_load_dwordx4 v[34:37], v[170:171], off offset:704
	s_waitcnt vmcnt(1)
	v_lshlrev_b32_e32 v51, 16, v38
	v_mul_f32_e32 v41, 0xbfb8aa3b, v51
	v_exp_f32_e32 v41, v41
	s_waitcnt vmcnt(0)
	v_mov_b32_e32 v50, v34
	v_mov_b32_e32 v42, v35
	v_add_f32_e32 v41, 1.0, v41
	v_rcp_f32_e32 v41, v41
	s_nop 0
	v_pk_mul_f32 v[40:41], v[40:41], v[50:51]
	s_nop 0
	v_mul_f32_e32 v50, v40, v41
	v_mul_f32_e32 v40, v43, v140
	v_and_b32_e32 v43, 0xffff0000, v38
	v_mul_f32_e32 v34, 0xbfb8aa3b, v43
	v_exp_f32_e32 v34, v34
	v_mov_b32_e32 v38, v37
	v_add_f32_e32 v34, 1.0, v34
	v_rcp_f32_e32 v41, v34
	s_nop 0
	v_pk_mul_f32 v[34:35], v[40:41], v[42:43]
	v_lshlrev_b32_e32 v41, 16, v39
	v_mul_f32_e32 v42, v34, v35
	v_mul_f32_e32 v35, 0xbfb8aa3b, v41
	v_exp_f32_e32 v35, v35
	v_mul_f32_e32 v34, v44, v140
	v_mov_b32_e32 v40, v36
	v_and_b32_e32 v39, 0xffff0000, v39
	v_add_f32_e32 v35, 1.0, v35
	v_rcp_f32_e32 v35, v35
	s_nop 0
	v_pk_mul_f32 v[34:35], v[34:35], v[40:41]
	s_nop 0
	v_mul_f32_e32 v36, v34, v35
	v_mul_f32_e32 v35, 0xbfb8aa3b, v39
	v_exp_f32_e32 v35, v35
	v_mul_f32_e32 v34, v45, v140
	v_mul_f32_e32 v40, v46, v140
	v_add_f32_e32 v35, 1.0, v35
	v_rcp_f32_e32 v35, v35
	s_nop 0
	v_pk_mul_f32 v[34:35], v[34:35], v[38:39]
	s_nop 0
	v_mul_f32_e32 v35, v34, v35
	v_cvt_pk_bf16_f32 v34, v50, v42
	v_cvt_pk_bf16_f32 v35, v36, v35
	global_store_dwordx2 v[134:135], v[34:35], off offset:352
	global_load_dwordx2 v[38:39], v[134:135], off offset:368
	s_nop 0
	global_load_dwordx4 v[34:37], v[170:171], off offset:736
	s_waitcnt vmcnt(1)
	v_lshlrev_b32_e32 v43, 16, v38
	v_mul_f32_e32 v41, 0xbfb8aa3b, v43
	v_exp_f32_e32 v41, v41
	s_waitcnt vmcnt(0)
	v_mov_b32_e32 v42, v34
	v_add_f32_e32 v41, 1.0, v41
	v_rcp_f32_e32 v41, v41
	s_nop 0
	v_pk_mul_f32 v[40:41], v[40:41], v[42:43]
	v_and_b32_e32 v43, 0xffff0000, v38
	v_mul_f32_e32 v34, 0xbfb8aa3b, v43
	v_exp_f32_e32 v34, v34
	v_mul_f32_e32 v44, v40, v41
	v_mul_f32_e32 v40, v47, v140
	v_mov_b32_e32 v42, v35
	v_add_f32_e32 v34, 1.0, v34
	v_rcp_f32_e32 v41, v34
	v_mov_b32_e32 v38, v37
	v_pk_mul_f32 v[34:35], v[40:41], v[42:43]
	v_lshlrev_b32_e32 v41, 16, v39
	v_mul_f32_e32 v42, v34, v35
	v_mul_f32_e32 v35, 0xbfb8aa3b, v41
	v_exp_f32_e32 v35, v35
	v_mul_f32_e32 v34, v48, v140
	v_mov_b32_e32 v40, v36
	v_and_b32_e32 v39, 0xffff0000, v39
	v_add_f32_e32 v35, 1.0, v35
	v_rcp_f32_e32 v35, v35
	s_nop 0
	v_pk_mul_f32 v[34:35], v[34:35], v[40:41]
	s_nop 0
	v_mul_f32_e32 v36, v34, v35
	v_mul_f32_e32 v35, 0xbfb8aa3b, v39
	v_exp_f32_e32 v35, v35
	v_mul_f32_e32 v34, v49, v140
	v_mul_f32_e32 v40, v18, v140
	v_add_f32_e32 v35, 1.0, v35
	v_rcp_f32_e32 v35, v35
	s_nop 0
	v_pk_mul_f32 v[34:35], v[34:35], v[38:39]
	s_nop 0
	v_mul_f32_e32 v35, v34, v35
	v_cvt_pk_bf16_f32 v34, v44, v42
	v_cvt_pk_bf16_f32 v35, v36, v35
	global_store_dwordx2 v[134:135], v[34:35], off offset:368
	global_load_dwordx2 v[38:39], v[134:135], off offset:384
	s_nop 0
	global_load_dwordx4 v[34:37], v[170:171], off offset:768
	s_waitcnt vmcnt(1)
; __device__ __forceinline__ unsigned cvt_pk_bf16(float lo, float hi) { unsigned r; asm volatile("v_cvt_pk_bf16_f32 %0, %1, %2" : "=v"(r) : "v"(lo), "v"(hi)); return r; }
; __device__ __forceinline__ float bf_lo(unsigned w) { return __uint_as_float(w << 16); }
; __device__ __forceinline__ float bf_hi(unsigned w) { return __uint_as_float(w & 0xffff0000u); }
; __device__ __forceinline__ float siluf_(float v) { return v * sigmoidf_(v); }
; __device__ __forceinline__ void gla_out(const Params& p, LAS unsigned char* lds, int l) {
;     ...
;             bf16_t* zp = proj + (size_t)(tok0 + 32 * ib + r32) * NP + C_ZC + h * 256; const float* gn = p.gla_norm + l * 1024 + h * 256;
; #pragma unroll
;             for (int dvb = 0; dvb < 8; ++dvb)
; #pragma unroll
;                 for (int rq = 0; rq < 4; ++rq) { const int dv = dvb * 32 + 8 * rq + 4 * hi; const u32x2 zz = *(const u32x2*)(zp + dv); const f32x4 g4 = *(const f32x4*)(gn + dv);
;                     const float y0 = o[dvb][rq * 4 + 0] * rs * g4[0] * siluf_(bf_lo(zz.x)), y1 = o[dvb][rq * 4 + 1] * rs * g4[1] * siluf_(bf_hi(zz.x));
;                     const float y2 = o[dvb][rq * 4 + 2] * rs * g4[2] * siluf_(bf_lo(zz.y)), y3 = o[dvb][rq * 4 + 3] * rs * g4[3] * siluf_(bf_hi(zz.y));
;                     u32x2 w; w.x = cvt_pk_bf16(y0, y1); w.y = cvt_pk_bf16(y2, y3); *(u32x2*)(zp + dv) = w; }
	v_lshlrev_b32_e32 v43, 16, v38
	v_mul_f32_e32 v18, 0xbfb8aa3b, v43
	v_exp_f32_e32 v18, v18
	s_waitcnt vmcnt(0)
	v_mov_b32_e32 v42, v34
	v_mov_b32_e32 v34, v36
	v_mul_f32_e32 v36, v22, v140
	v_add_f32_e32 v18, 1.0, v18
	v_rcp_f32_e32 v41, v18
	v_mul_f32_e32 v18, v19, v140
	v_pk_mul_f32 v[40:41], v[40:41], v[42:43]
	s_nop 0
	v_mul_f32_e32 v42, v40, v41
	v_and_b32_e32 v41, 0xffff0000, v38
	v_mul_f32_e32 v19, 0xbfb8aa3b, v41
	v_exp_f32_e32 v19, v19
	v_mov_b32_e32 v40, v35
	v_lshlrev_b32_e32 v35, 16, v39
	v_add_f32_e32 v19, 1.0, v19
	v_rcp_f32_e32 v19, v19
	s_nop 0
	v_pk_mul_f32 v[18:19], v[18:19], v[40:41]
	s_nop 0
	v_mul_f32_e32 v38, v18, v19
	v_mul_f32_e32 v19, 0xbfb8aa3b, v35
	v_exp_f32_e32 v19, v19
	v_mul_f32_e32 v18, v20, v140
	v_mov_b32_e32 v20, v37
	v_add_f32_e32 v19, 1.0, v19
	v_rcp_f32_e32 v19, v19
	s_nop 0
	v_pk_mul_f32 v[18:19], v[18:19], v[34:35]
	s_nop 0
	v_mul_f32_e32 v34, v18, v19
	v_mul_f32_e32 v18, v21, v140
	v_and_b32_e32 v21, 0xffff0000, v39
	v_mul_f32_e32 v19, 0xbfb8aa3b, v21
	v_exp_f32_e32 v19, v19
	s_nop 0
	v_add_f32_e32 v19, 1.0, v19
	v_rcp_f32_e32 v19, v19
	s_nop 0
	v_pk_mul_f32 v[18:19], v[18:19], v[20:21]
	s_nop 0
	v_mul_f32_e32 v19, v18, v19
	v_cvt_pk_bf16_f32 v18, v42, v38
	v_cvt_pk_bf16_f32 v19, v34, v19
	global_store_dwordx2 v[134:135], v[18:19], off offset:384
	global_load_dwordx2 v[34:35], v[134:135], off offset:400
	s_nop 0
	global_load_dwordx4 v[18:21], v[170:171], off offset:800
	s_waitcnt vmcnt(1)
	v_lshlrev_b32_e32 v39, 16, v34
	v_mul_f32_e32 v22, 0xbfb8aa3b, v39
	v_exp_f32_e32 v22, v22
	s_waitcnt vmcnt(0)
	v_mov_b32_e32 v38, v18
	v_add_f32_e32 v22, 1.0, v22
	v_rcp_f32_e32 v37, v22
	v_mul_f32_e32 v22, v23, v140
	v_pk_mul_f32 v[36:37], v[36:37], v[38:39]
	s_nop 0
	v_mul_f32_e32 v38, v36, v37
	v_and_b32_e32 v37, 0xffff0000, v34
	v_mul_f32_e32 v18, 0xbfb8aa3b, v37
	v_exp_f32_e32 v18, v18
	v_mov_b32_e32 v36, v19
	v_add_f32_e32 v18, 1.0, v18
	v_rcp_f32_e32 v23, v18
	s_nop 0
	v_pk_mul_f32 v[18:19], v[22:23], v[36:37]
	v_lshlrev_b32_e32 v23, 16, v35
	v_mul_f32_e32 v34, v18, v19
	v_mul_f32_e32 v19, 0xbfb8aa3b, v23
	v_exp_f32_e32 v19, v19
	v_mul_f32_e32 v18, v24, v140
	v_mov_b32_e32 v22, v20
	v_mul_f32_e32 v24, v26, v140
	v_add_f32_e32 v19, 1.0, v19
	v_rcp_f32_e32 v19, v19
	s_nop 0
	v_pk_mul_f32 v[18:19], v[18:19], v[22:23]
	v_and_b32_e32 v23, 0xffff0000, v35
	v_mul_f32_e32 v20, v18, v19
	v_mul_f32_e32 v19, 0xbfb8aa3b, v23
	v_exp_f32_e32 v19, v19
	v_mul_f32_e32 v18, v25, v140
	v_mov_b32_e32 v22, v21
	v_add_f32_e32 v19, 1.0, v19
	v_rcp_f32_e32 v19, v19
	s_nop 0
	v_pk_mul_f32 v[18:19], v[18:19], v[22:23]
	s_nop 0
	v_mul_f32_e32 v19, v18, v19
	v_cvt_pk_bf16_f32 v18, v38, v34
	v_cvt_pk_bf16_f32 v19, v20, v19
	global_store_dwordx2 v[134:135], v[18:19], off offset:400
	global_load_dwordx2 v[22:23], v[134:135], off offset:416
	s_nop 0
	global_load_dwordx4 v[18:21], v[170:171], off offset:832
	s_waitcnt vmcnt(1)
	v_lshlrev_b32_e32 v35, 16, v22
	v_mul_f32_e32 v25, 0xbfb8aa3b, v35
	v_exp_f32_e32 v25, v25
	s_waitcnt vmcnt(0)
	v_mov_b32_e32 v34, v18
	v_mov_b32_e32 v26, v19
	v_add_f32_e32 v25, 1.0, v25
	v_rcp_f32_e32 v25, v25
	s_nop 0
	v_pk_mul_f32 v[24:25], v[24:25], v[34:35]
	s_nop 0
	v_mul_f32_e32 v34, v24, v25
	v_mul_f32_e32 v24, v27, v140
	v_and_b32_e32 v27, 0xffff0000, v22
	v_mul_f32_e32 v18, 0xbfb8aa3b, v27
	v_exp_f32_e32 v18, v18
	v_mov_b32_e32 v22, v21
	v_add_f32_e32 v18, 1.0, v18
	v_rcp_f32_e32 v25, v18
	s_nop 0
	v_pk_mul_f32 v[18:19], v[24:25], v[26:27]
	v_lshlrev_b32_e32 v25, 16, v23
	v_mul_f32_e32 v26, v18, v19
	v_mul_f32_e32 v19, 0xbfb8aa3b, v25
	v_exp_f32_e32 v19, v19
	v_mul_f32_e32 v18, v28, v140
	v_mov_b32_e32 v24, v20
	v_and_b32_e32 v23, 0xffff0000, v23
	v_add_f32_e32 v19, 1.0, v19
	v_rcp_f32_e32 v19, v19
	s_nop 0
	v_pk_mul_f32 v[18:19], v[18:19], v[24:25]
	s_nop 0
	v_mul_f32_e32 v20, v18, v19
	v_mul_f32_e32 v19, 0xbfb8aa3b, v23
	v_exp_f32_e32 v19, v19
	v_mul_f32_e32 v18, v29, v140
	v_mul_f32_e32 v24, v30, v140
	v_add_f32_e32 v19, 1.0, v19
	v_rcp_f32_e32 v19, v19
	s_nop 0
	v_pk_mul_f32 v[18:19], v[18:19], v[22:23]
	s_nop 0
	v_mul_f32_e32 v19, v18, v19
	v_cvt_pk_bf16_f32 v18, v34, v26
	v_cvt_pk_bf16_f32 v19, v20, v19
	global_store_dwordx2 v[134:135], v[18:19], off offset:416
	global_load_dwordx2 v[22:23], v[134:135], off offset:432
	s_nop 0
	global_load_dwordx4 v[18:21], v[170:171], off offset:864
	s_waitcnt vmcnt(1)
	v_lshlrev_b32_e32 v27, 16, v22
	v_mul_f32_e32 v25, 0xbfb8aa3b, v27
	v_exp_f32_e32 v25, v25
	s_waitcnt vmcnt(0)
	v_mov_b32_e32 v26, v18
	v_add_f32_e32 v25, 1.0, v25
	v_rcp_f32_e32 v25, v25
	s_nop 0
	v_pk_mul_f32 v[24:25], v[24:25], v[26:27]
	v_and_b32_e32 v27, 0xffff0000, v22
	v_mul_f32_e32 v18, 0xbfb8aa3b, v27
	v_exp_f32_e32 v18, v18
	v_mul_f32_e32 v28, v24, v25
	v_mul_f32_e32 v24, v31, v140
	v_mov_b32_e32 v26, v19
	v_add_f32_e32 v18, 1.0, v18
	v_rcp_f32_e32 v25, v18
	v_mov_b32_e32 v22, v21
	v_pk_mul_f32 v[18:19], v[24:25], v[26:27]
	v_lshlrev_b32_e32 v25, 16, v23
	v_mul_f32_e32 v26, v18, v19
	v_mul_f32_e32 v19, 0xbfb8aa3b, v25
	v_exp_f32_e32 v19, v19
	v_mul_f32_e32 v18, v32, v140
	v_mov_b32_e32 v24, v20
	v_and_b32_e32 v23, 0xffff0000, v23
	v_add_f32_e32 v19, 1.0, v19
	v_rcp_f32_e32 v19, v19
	s_nop 0
	v_pk_mul_f32 v[18:19], v[18:19], v[24:25]
	s_nop 0
	v_mul_f32_e32 v20, v18, v19
	v_mul_f32_e32 v19, 0xbfb8aa3b, v23
	v_exp_f32_e32 v19, v19
	v_mul_f32_e32 v18, v33, v140
	v_mul_f32_e32 v24, v2, v140
	v_add_f32_e32 v19, 1.0, v19
	v_rcp_f32_e32 v19, v19
	s_nop 0
	v_pk_mul_f32 v[18:19], v[18:19], v[22:23]
	s_nop 0
	v_mul_f32_e32 v19, v18, v19
	v_cvt_pk_bf16_f32 v18, v28, v26
	v_cvt_pk_bf16_f32 v19, v20, v19
	global_store_dwordx2 v[134:135], v[18:19], off offset:432
	global_load_dwordx2 v[22:23], v[134:135], off offset:448
	s_nop 0
	global_load_dwordx4 v[18:21], v[170:171], off offset:896
	s_waitcnt vmcnt(1)
; __device__ __forceinline__ unsigned cvt_pk_bf16(float lo, float hi) { unsigned r; asm volatile("v_cvt_pk_bf16_f32 %0, %1, %2" : "=v"(r) : "v"(lo), "v"(hi)); return r; }
; __device__ __forceinline__ float bf_lo(unsigned w) { return __uint_as_float(w << 16); }
; __device__ __forceinline__ float bf_hi(unsigned w) { return __uint_as_float(w & 0xffff0000u); }
; __device__ __forceinline__ float siluf_(float v) { return v * sigmoidf_(v); }
; __device__ __forceinline__ void gla_out(const Params& p, LAS unsigned char* lds, int l) {
;     ...
;             bf16_t* zp = proj + (size_t)(tok0 + 32 * ib + r32) * NP + C_ZC + h * 256; const float* gn = p.gla_norm + l * 1024 + h * 256;
; #pragma unroll
;             for (int dvb = 0; dvb < 8; ++dvb)
; #pragma unroll
;                 for (int rq = 0; rq < 4; ++rq) { const int dv = dvb * 32 + 8 * rq + 4 * hi; const u32x2 zz = *(const u32x2*)(zp + dv); const f32x4 g4 = *(const f32x4*)(gn + dv);
;                     const float y0 = o[dvb][rq * 4 + 0] * rs * g4[0] * siluf_(bf_lo(zz.x)), y1 = o[dvb][rq * 4 + 1] * rs * g4[1] * siluf_(bf_hi(zz.x));
;                     const float y2 = o[dvb][rq * 4 + 2] * rs * g4[2] * siluf_(bf_lo(zz.y)), y3 = o[dvb][rq * 4 + 3] * rs * g4[3] * siluf_(bf_hi(zz.y));
;                     u32x2 w; w.x = cvt_pk_bf16(y0, y1); w.y = cvt_pk_bf16(y2, y3); *(u32x2*)(zp + dv) = w; }
;         }
;         __syncthreads();
;     }
; }
	v_lshlrev_b32_e32 v27, 16, v22
	v_mul_f32_e32 v2, 0xbfb8aa3b, v27
	v_exp_f32_e32 v2, v2
	s_waitcnt vmcnt(0)
	v_mov_b32_e32 v26, v18
	v_mov_b32_e32 v18, v20
	v_mul_f32_e32 v20, v6, v140
	v_add_f32_e32 v2, 1.0, v2
	v_rcp_f32_e32 v25, v2
	v_mul_f32_e32 v2, v3, v140
	v_pk_mul_f32 v[24:25], v[24:25], v[26:27]
	s_nop 0
	v_mul_f32_e32 v26, v24, v25
	v_and_b32_e32 v25, 0xffff0000, v22
	v_mul_f32_e32 v3, 0xbfb8aa3b, v25
	v_exp_f32_e32 v3, v3
	v_mov_b32_e32 v24, v19
	v_lshlrev_b32_e32 v19, 16, v23
	v_add_f32_e32 v3, 1.0, v3
	v_rcp_f32_e32 v3, v3
	s_nop 0
	v_pk_mul_f32 v[2:3], v[2:3], v[24:25]
	s_nop 0
	v_mul_f32_e32 v22, v2, v3
	v_mul_f32_e32 v3, 0xbfb8aa3b, v19
	v_exp_f32_e32 v3, v3
	v_mul_f32_e32 v2, v4, v140
	v_mov_b32_e32 v4, v21
	v_add_f32_e32 v3, 1.0, v3
	v_rcp_f32_e32 v3, v3
	s_nop 0
	v_pk_mul_f32 v[2:3], v[2:3], v[18:19]
	s_nop 0
	v_mul_f32_e32 v18, v2, v3
	v_mul_f32_e32 v2, v5, v140
	v_and_b32_e32 v5, 0xffff0000, v23
	v_mul_f32_e32 v3, 0xbfb8aa3b, v5
	v_exp_f32_e32 v3, v3
	s_nop 0
	v_add_f32_e32 v3, 1.0, v3
	v_rcp_f32_e32 v3, v3
	s_nop 0
	v_pk_mul_f32 v[2:3], v[2:3], v[4:5]
	s_nop 0
	v_mul_f32_e32 v3, v2, v3
	v_cvt_pk_bf16_f32 v2, v26, v22
	v_cvt_pk_bf16_f32 v3, v18, v3
	global_store_dwordx2 v[134:135], v[2:3], off offset:448
	global_load_dwordx2 v[18:19], v[134:135], off offset:464
	s_nop 0
	global_load_dwordx4 v[2:5], v[170:171], off offset:928
	s_waitcnt vmcnt(1)
	v_lshlrev_b32_e32 v23, 16, v18
	v_mul_f32_e32 v6, 0xbfb8aa3b, v23
	v_exp_f32_e32 v6, v6
	s_waitcnt vmcnt(0)
	v_mov_b32_e32 v22, v2
	v_add_f32_e32 v6, 1.0, v6
	v_rcp_f32_e32 v21, v6
	v_mul_f32_e32 v6, v7, v140
	v_pk_mul_f32 v[20:21], v[20:21], v[22:23]
	s_nop 0
	v_mul_f32_e32 v22, v20, v21
	v_and_b32_e32 v21, 0xffff0000, v18
	v_mul_f32_e32 v2, 0xbfb8aa3b, v21
	v_exp_f32_e32 v2, v2
	v_mov_b32_e32 v20, v3
	v_add_f32_e32 v2, 1.0, v2
	v_rcp_f32_e32 v7, v2
	s_nop 0
	v_pk_mul_f32 v[2:3], v[6:7], v[20:21]
	v_lshlrev_b32_e32 v7, 16, v19
	v_mul_f32_e32 v18, v2, v3
	v_mul_f32_e32 v3, 0xbfb8aa3b, v7
	v_exp_f32_e32 v3, v3
	v_mul_f32_e32 v2, v8, v140
	v_mov_b32_e32 v6, v4
	v_mul_f32_e32 v8, v10, v140
	v_add_f32_e32 v3, 1.0, v3
	v_rcp_f32_e32 v3, v3
	s_nop 0
	v_pk_mul_f32 v[2:3], v[2:3], v[6:7]
	v_and_b32_e32 v7, 0xffff0000, v19
	v_mul_f32_e32 v4, v2, v3
	v_mul_f32_e32 v3, 0xbfb8aa3b, v7
	v_exp_f32_e32 v3, v3
	v_mul_f32_e32 v2, v9, v140
	v_mov_b32_e32 v6, v5
	v_add_f32_e32 v3, 1.0, v3
	v_rcp_f32_e32 v3, v3
	s_nop 0
	v_pk_mul_f32 v[2:3], v[2:3], v[6:7]
	s_nop 0
	v_mul_f32_e32 v3, v2, v3
	v_cvt_pk_bf16_f32 v2, v22, v18
	v_cvt_pk_bf16_f32 v3, v4, v3
	global_store_dwordx2 v[134:135], v[2:3], off offset:464
	global_load_dwordx2 v[6:7], v[134:135], off offset:480
	s_nop 0
	global_load_dwordx4 v[2:5], v[170:171], off offset:960
	s_waitcnt vmcnt(1)
	v_lshlrev_b32_e32 v19, 16, v6
	v_mul_f32_e32 v9, 0xbfb8aa3b, v19
	v_exp_f32_e32 v9, v9
	s_waitcnt vmcnt(0)
	v_mov_b32_e32 v18, v2
	v_mov_b32_e32 v10, v3
	v_add_f32_e32 v9, 1.0, v9
	v_rcp_f32_e32 v9, v9
	s_nop 0
	v_pk_mul_f32 v[8:9], v[8:9], v[18:19]
	s_nop 0
	v_mul_f32_e32 v18, v8, v9
	v_mul_f32_e32 v8, v11, v140
	v_and_b32_e32 v11, 0xffff0000, v6
	v_mul_f32_e32 v2, 0xbfb8aa3b, v11
	v_exp_f32_e32 v2, v2
	v_mov_b32_e32 v6, v5
	v_add_f32_e32 v2, 1.0, v2
	v_rcp_f32_e32 v9, v2
	s_nop 0
	v_pk_mul_f32 v[2:3], v[8:9], v[10:11]
	v_lshlrev_b32_e32 v9, 16, v7
	v_mul_f32_e32 v10, v2, v3
	v_mul_f32_e32 v3, 0xbfb8aa3b, v9
	v_exp_f32_e32 v3, v3
	v_mul_f32_e32 v2, v12, v140
	v_mov_b32_e32 v8, v4
	v_and_b32_e32 v7, 0xffff0000, v7
	v_add_f32_e32 v3, 1.0, v3
	v_rcp_f32_e32 v3, v3
	s_nop 0
	v_pk_mul_f32 v[2:3], v[2:3], v[8:9]
	s_nop 0
	v_mul_f32_e32 v4, v2, v3
	v_mul_f32_e32 v3, 0xbfb8aa3b, v7
	v_exp_f32_e32 v3, v3
	v_mul_f32_e32 v2, v13, v140
	v_mul_f32_e32 v8, v14, v140
	v_add_f32_e32 v3, 1.0, v3
	v_rcp_f32_e32 v3, v3
	s_nop 0
	v_pk_mul_f32 v[2:3], v[2:3], v[6:7]
	s_nop 0
	v_mul_f32_e32 v3, v2, v3
	v_cvt_pk_bf16_f32 v2, v18, v10
	v_cvt_pk_bf16_f32 v3, v4, v3
	global_store_dwordx2 v[134:135], v[2:3], off offset:480
	global_load_dwordx2 v[6:7], v[134:135], off offset:496
	s_nop 0
	global_load_dwordx4 v[2:5], v[170:171], off offset:992
	s_waitcnt vmcnt(1)
	v_lshlrev_b32_e32 v11, 16, v6
	v_mul_f32_e32 v9, 0xbfb8aa3b, v11
	v_exp_f32_e32 v9, v9
	s_waitcnt vmcnt(0)
	v_mov_b32_e32 v10, v2
	v_add_f32_e32 v9, 1.0, v9
	v_rcp_f32_e32 v9, v9
	s_nop 0
	v_pk_mul_f32 v[8:9], v[8:9], v[10:11]
	v_and_b32_e32 v11, 0xffff0000, v6
	v_mul_f32_e32 v2, 0xbfb8aa3b, v11
	v_exp_f32_e32 v2, v2
	v_mul_f32_e32 v12, v8, v9
	v_mul_f32_e32 v8, v15, v140
	v_mov_b32_e32 v10, v3
	v_add_f32_e32 v2, 1.0, v2
	v_rcp_f32_e32 v9, v2
	v_mov_b32_e32 v6, v5
	v_pk_mul_f32 v[2:3], v[8:9], v[10:11]
	v_lshlrev_b32_e32 v9, 16, v7
	v_mul_f32_e32 v10, v2, v3
	v_mul_f32_e32 v3, 0xbfb8aa3b, v9
	v_exp_f32_e32 v3, v3
	v_mul_f32_e32 v2, v16, v140
	v_mov_b32_e32 v8, v4
	v_and_b32_e32 v7, 0xffff0000, v7
	v_add_f32_e32 v3, 1.0, v3
	v_rcp_f32_e32 v3, v3
	s_nop 0
	v_pk_mul_f32 v[2:3], v[2:3], v[8:9]
	s_nop 0
	v_mul_f32_e32 v4, v2, v3
	v_mul_f32_e32 v3, 0xbfb8aa3b, v7
	v_exp_f32_e32 v3, v3
	v_mul_f32_e32 v2, v17, v140
	v_add_f32_e32 v3, 1.0, v3
	v_rcp_f32_e32 v3, v3
	s_nop 0
	v_pk_mul_f32 v[2:3], v[2:3], v[6:7]
	s_nop 0
	v_mul_f32_e32 v3, v2, v3
	v_cvt_pk_bf16_f32 v2, v12, v10
	v_cvt_pk_bf16_f32 v3, v4, v3
	global_store_dwordx2 v[134:135], v[2:3], off offset:496
	s_barrier
	s_add_i32 s34, s0, s34
	s_cmpk_gt_i32 s34, 0xff
	s_cbranch_scc1 .LBB0_366
